# rwkv_prep_item: dropped logf denormal pre-scale / inf select around 31 softplus log(1+exp(-|x|)) terms (argument in [1,2], exact), on top of v049
# baseline (speedup 1.0000x reference)
; __device__ __forceinline__ void rwkv_prep_item(KArgs a, int l, int item, LAS unsigned char* lds, int tid, int lane, int wave) {
;     ...
;         const float rn = rsqrtf(row16_sum(ss) + 1e-12f);
;         float bon = 0.f;
; #pragma unroll
;         for (int nt = 0; nt < 4; ++nt) { const int c = 64 * wave + 16 * nt + fr;
;             Wd[0][i][nt] = __expf(-__expf(-softplusf_(-(w0f[nt] + acc[0][nt][i])) - 0.5f)); Wd[1][i][nt] = __expf(-__expf(-softplusf_(-(w0b[nt] + acc[1][nt][i])) - 0.5f));
;             const float kk = kkv[nt] * rn; Km[i][nt] = k[nt] * (1.f + (av[nt] - 1.f) * kac[nt]); Ka[i][nt] = kk * av[nt]; Nn[i][nt] = -kk;
;             bon += Rr[i][nt] * Km[i][nt] * rkc[nt];
;             float* o = RW + R * 512 + c; o[7 * AS] = Vv[i][nt]; o[8 * AS] = acc[3][nt][i]; }
;         bon = row16_sum(bon);
;         if (fr == 0) RSC[(size_t)2 * TT * 8 + R * 8 + h] = bon;
;     }
;     __syncthreads();
;     LAS unsigned char* wl_ = lds + wave * 14336;
;     LAS bf16* NTl = (LAS bf16*)wl_; LAS bf16* RTl = NTl + 16 * 68; LAS bf16* ATl = RTl + 16 * 68; LAS bf16* KTl = ATl + 16 * 68;
;     LAS float* ASl = (LAS float*)(wl_ + 8704);
;     LAS float* TTl = (LAS float*)(wl_ + 11264);
;     typedef short bf16x4 __attribute__((ext_vector_type(4)));
; #pragma unroll
;     for (int d = 0; d < 2; ++d) {
;         const int cidx = d ? (isctx ? (240 - j0) / 16 : (2544 - j0) / 16) : j0 / 16;
;         unsigned char* img = ws + OFF_RCH + ((size_t)((b * 2 + d) * 8 + h) * 144 + cidx) * RCH_BYTES;
;         const int laneD = d ? ((3 - fq) * 16 + fr) : lane;
; #pragma unroll
;         for (int nt = 0; nt < 4; ++nt) {
;             float gam[4], gpv[4], G, E;
;             if (d == 0) { gam[0] = Wd[0][0][nt]; gam[1] = gam[0] * Wd[0][1][nt]; gam[2] = gam[1] * Wd[0][2][nt]; gam[3] = gam[2] * Wd[0][3][nt]; G = gam[3];
;                 const float g1 = __int_as_float(__builtin_amdgcn_ds_bpermute((lane - 16) << 2, __float_as_int(G))), g2 = __int_as_float(__builtin_amdgcn_ds_bpermute((lane - 32) << 2, __float_as_int(G))), g3 = __int_as_float(__builtin_amdgcn_ds_bpermute((lane - 48) << 2, __float_as_int(G)));
;                 E = (fq >= 1 ? g1 : 1.f) * (fq >= 2 ? g2 : 1.f) * (fq >= 3 ? g3 : 1.f);
;                 gpv[0] = E; gpv[1] = E * gam[0]; gpv[2] = E * gam[1]; gpv[3] = E * gam[2];
; #pragma unroll
;                 for (int i = 0; i < 4; ++i) gam[i] *= E; }
.LBB0_834:
	s_or_b64 exec, exec, s[0:1]
	v_add_f32_e32 v2, v145, v122
	v_mul_f32_e64 v3, |v2|, s16
	v_exp_f32_e32 v3, v3
	v_add_f32_e32 v5, v31, v67
	v_add_f32_e32 v5, 0x2b8cbccc, v5
	v_mul_f32_e32 v31, 0x4b800000, v5
	v_add_f32_e32 v3, 1.0, v3
	v_cmp_gt_f32_e64 s[44:45], s30, v5
	s_mov_b32 s0, 0x3f317217
	v_log_f32_e32 v3, v3
	v_cndmask_b32_e64 v5, v5, v31, s[44:45]
	s_mov_b32 s1, 0x7f800000
	v_max_f32_e64 v2, -v2, 0
	v_mul_f32_e32 v31, 0x3f317217, v3
	v_fma_f32 v31, v3, s0, -v31
	v_fmac_f32_e32 v31, 0x3377d1cf, v3
	v_fmac_f32_e32 v31, 0x3f317217, v3
	v_rsq_f32_e32 v5, v5
	v_cmp_lt_i32_e64 s[48:49], 1, v184
	v_mov_b32_e32 v3, v31
	v_add_f32_e32 v2, v2, v3
	v_sub_f32_e32 v2, -0.5, v2
	v_mul_f32_e32 v2, 0x3fb8aa3b, v2
	v_exp_f32_e32 v2, v2
	v_mul_f32_e32 v3, 0x45800000, v5
	v_cndmask_b32_e64 v151, v5, v3, s[44:45]
	v_add_f32_e32 v5, v39, v61
	v_mul_f32_e32 v2, 0xbfb8aa3b, v2
	v_exp_f32_e32 v68, v2
	v_add_f32_e32 v2, v144, v122
	v_mul_f32_e64 v3, |v2|, s16
	v_exp_f32_e32 v3, v3
	v_add_f32_e32 v5, 0x2b8cbccc, v5
	v_mul_f32_e32 v39, 0x4b800000, v5
	v_cmp_gt_f32_e64 s[44:45], s30, v5
	v_add_f32_e32 v3, 1.0, v3
	s_nop 0
	v_cndmask_b32_e64 v5, v5, v39, s[44:45]
	v_max_f32_e64 v2, -v2, 0
	v_log_f32_e32 v3, v3
	v_rsq_f32_e32 v5, v5
	v_mul_f32_e32 v31, v74, v151
	v_mul_f32_e32 v73, v4, v31
	v_mul_f32_e32 v39, 0x3f317217, v3
	v_fma_f32 v39, v3, s0, -v39
	v_fmac_f32_e32 v39, 0x3377d1cf, v3
	v_fmac_f32_e32 v39, 0x3f317217, v3
	v_add_f32_e32 v4, v57, v159
	v_add_f32_e32 v4, 0x2b8cbccc, v4
	v_mov_b32_e32 v3, v39
	v_add_f32_e32 v2, v2, v3
	v_sub_f32_e32 v2, -0.5, v2
	v_mul_f32_e32 v2, 0x3fb8aa3b, v2
	v_exp_f32_e32 v2, v2
	v_mul_f32_e32 v3, 0x45800000, v5
	v_cndmask_b32_e64 v87, v5, v3, s[44:45]
	v_mul_f32_e32 v5, 0x4b800000, v4
	v_mul_f32_e32 v2, 0xbfb8aa3b, v2
	v_exp_f32_e32 v69, v2
	v_add_f32_e32 v2, v143, v122
	v_mul_f32_e64 v3, |v2|, s16
	v_exp_f32_e32 v3, v3
	v_cmp_gt_f32_e64 s[44:45], s30, v4
	v_max_f32_e64 v2, -v2, 0
	v_mul_f32_e32 v39, v70, v87
	v_add_f32_e32 v3, 1.0, v3
	v_cndmask_b32_e64 v4, v4, v5, s[44:45]
	v_rsq_f32_e32 v4, v4
	v_log_f32_e32 v3, v3
	v_mul_f32_e32 v72, v7, v39
	v_lshlrev_b32_e32 v61, 2, v182
	v_subrev_u32_e32 v143, 64, v61
	v_mul_f32_e32 v5, 0x3f317217, v3
	v_fma_f32 v5, v3, s0, -v5
	v_fmac_f32_e32 v5, 0x3377d1cf, v3
	v_fmac_f32_e32 v5, 0x3f317217, v3
	v_add_u32_e32 v144, 0xffffff80, v61
	v_xor_b32_e32 v67, 64, v61
	v_mov_b32_e32 v3, v5
	v_add_f32_e32 v2, v2, v3
	v_sub_f32_e32 v2, -0.5, v2
	v_mul_f32_e32 v2, 0x3fb8aa3b, v2
	v_exp_f32_e32 v2, v2
	v_mul_f32_e32 v3, 0x45800000, v4
	v_cndmask_b32_e64 v147, v4, v3, s[44:45]
	v_add_f32_e32 v4, v92, v93
	v_mul_f32_e32 v2, 0xbfb8aa3b, v2
	v_exp_f32_e32 v70, v2
	v_add_f32_e32 v2, v142, v122
	v_mul_f32_e64 v3, |v2|, s16
	v_exp_f32_e32 v3, v3
	v_add_f32_e32 v4, 0x2b8cbccc, v4
	v_mul_f32_e32 v5, 0x4b800000, v4
	v_cmp_gt_f32_e64 s[44:45], s30, v4
	v_add_f32_e32 v3, 1.0, v3
	s_nop 0
	v_cndmask_b32_e64 v4, v4, v5, s[44:45]
	v_max_f32_e64 v2, -v2, 0
	v_log_f32_e32 v3, v3
	v_rsq_f32_e32 v4, v4
	v_mul_f32_e32 v57, v78, v147
	v_add_u32_e32 v142, 0xffffff40, v61
	v_mul_f32_e32 v5, 0x3f317217, v3
	v_fma_f32 v5, v3, s0, -v5
	v_fmac_f32_e32 v5, 0x3377d1cf, v3
	v_fmac_f32_e32 v5, 0x3f317217, v3
	s_lshl_b32 s2, s8, 4
	v_cmp_lt_i32_e64 s[50:51], 2, v184
	v_mov_b32_e32 v3, v5
	v_add_f32_e32 v2, v2, v3
	v_sub_f32_e32 v2, -0.5, v2
	v_mul_f32_e32 v2, 0x3fb8aa3b, v2
	v_exp_f32_e32 v2, v2
	v_mul_f32_e32 v3, 0x45800000, v4
	v_cndmask_b32_e64 v145, v4, v3, s[44:45]
	v_mul_f32_e32 v124, v96, v145
	v_mul_f32_e32 v2, 0xbfb8aa3b, v2
	v_exp_f32_e32 v74, v2
	v_mul_f32_e32 v76, v54, v124
	v_cmp_lt_i32_e64 s[46:47], 0, v184
	s_add_i32 s2, s2, s28
	v_mul_f32_e32 v70, v74, v70
	v_mul_f32_e32 v69, v69, v70
	v_mul_f32_e32 v68, v68, v69
	ds_bpermute_b32 v54, v143, v68
	ds_bpermute_b32 v78, v144, v68
	ds_bpermute_b32 v80, v142, v68
	v_xor_b32_e32 v7, 0x80, v61
	s_mul_i32 s1, s2, 0x90
	s_waitcnt lgkmcnt(2)
	v_cndmask_b32_e64 v54, 1.0, v54, s[46:47]
	s_waitcnt lgkmcnt(1)
	v_cndmask_b32_e64 v78, 1.0, v78, s[48:49]
	v_mul_f32_e32 v54, v54, v78
	ds_bpermute_b32 v78, v67, v68
	s_waitcnt lgkmcnt(1)
	v_cndmask_b32_e64 v80, 1.0, v80, s[50:51]
	s_ashr_i32 s3, s7, 31
	v_mul_f32_e32 v92, v54, v80
	s_mul_hi_i32 s0, s2, 0x90
	s_waitcnt lgkmcnt(0)
	v_mul_f32_e32 v54, v68, v78
	s_add_u32 s1, s1, s7
	v_mul_f32_e32 v74, v74, v92
	ds_bpermute_b32 v80, v7, v54
	s_addc_u32 s0, s0, s3
	v_rcp_f32_e32 v81, v74
	s_mulk_i32 s0, 0x3100
	s_mul_hi_u32 s3, s1, 0x3100
	s_add_i32 s3, s3, s0
	s_mulk_i32 s1, 0x3100
	v_readlane_b32 s4, v254, 41
	v_lshlrev_b32_e32 v4, 3, v182
	v_readlane_b32 s5, v254, 42
	s_add_u32 s0, s4, s1
	v_ashrrev_i32_e32 v5, 31, v4
	s_addc_u32 s1, s5, s3
	v_mul_f32_e32 v96, v69, v92
	v_mul_f32_e32 v119, v68, v92
	s_waitcnt lgkmcnt(0)
	v_pk_mul_f32 v[68:69], v[54:55], v[80:81]
	v_mul_f32_e64 v54, v92, -v124
	v_lshl_add_u64 v[2:3], s[0:1], 0, v[4:5]
	s_add_u32 s4, s0, 0x3000
	v_cvt_pk_bf16_f32 v54, v54, s0
	s_movk_i32 s0, 0x110
	v_mul_f32_e32 v78, v70, v92
	v_mul_lo_u32 v70, v184, s0
	v_or_b32_e32 v80, v70, v0
	v_rcp_f32_e32 v93, v78
	v_mul_f32_e32 v77, v94, v57
	v_lshl_add_u32 v94, v80, 1, s25
	s_barrier
; __device__ __forceinline__ unsigned pk2(float lo, float hi) { const bf16x2_t r = __builtin_convertvector((f32x2){lo, hi}, bf16x2_t); return __builtin_bit_cast(unsigned, r); }
; __device__ __forceinline__ float softplusf_(float x) { return fmaxf(x, 0.f) + __logf(1.f + __expf(-fabsf(x))); }
; __device__ __forceinline__ void rwkv_prep_item(KArgs a, int l, int item, LAS unsigned char* lds, int tid, int lane, int wave) {
;     ...
;         const float rn = rsqrtf(row16_sum(ss) + 1e-12f);
;         float bon = 0.f;
; #pragma unroll
;         for (int nt = 0; nt < 4; ++nt) { const int c = 64 * wave + 16 * nt + fr;
;             Wd[0][i][nt] = __expf(-__expf(-softplusf_(-(w0f[nt] + acc[0][nt][i])) - 0.5f)); Wd[1][i][nt] = __expf(-__expf(-softplusf_(-(w0b[nt] + acc[1][nt][i])) - 0.5f));
;             const float kk = kkv[nt] * rn; Km[i][nt] = k[nt] * (1.f + (av[nt] - 1.f) * kac[nt]); Ka[i][nt] = kk * av[nt]; Nn[i][nt] = -kk;
;     ...
;             float tot = G * __int_as_float(__builtin_amdgcn_ds_bpermute((lane ^ 16) << 2, __float_as_int(G)));
;             tot = tot * __int_as_float(__builtin_amdgcn_ds_bpermute((lane ^ 32) << 2, __float_as_int(tot)));
;             float ap[4], kp[4];
; #pragma unroll
;             for (int i = 0; i < 4; ++i) { const int td = d ? 15 - (4 * fq + i) : 4 * fq + i; const float ig = __builtin_amdgcn_rcpf(gam[i]);
;                 const float at_ = Ka[i][nt] * ig, kt_ = Km[i][nt] * ig; ap[i] = at_ * tot; kp[i] = kt_ * tot;
;                 NTl[td * 68 + 16 * nt + fr] = bf1(gpv[i] * Nn[i][nt]); RTl[td * 68 + 16 * nt + fr] = bf1(gam[i] * Rr[i][nt]);
;                 ATl[td * 68 + 16 * nt + fr] = bf1(at_); KTl[td * 68 + 16 * nt + fr] = bf1(kt_); }
;             v2u pa, pk, pv;
;             if (d == 0) { pa = (v2u){pk2(ap[0], ap[1]), pk2(ap[2], ap[3])}; pk = (v2u){pk2(kp[0], kp[1]), pk2(kp[2], kp[3])}; pv = (v2u){pk2(Vv[0][nt], Vv[1][nt]), pk2(Vv[2][nt], Vv[3][nt])}; }
;             else { pa = (v2u){pk2(ap[3], ap[2]), pk2(ap[1], ap[0])}; pk = (v2u){pk2(kp[3], kp[2]), pk2(kp[1], kp[0])}; pv = (v2u){pk2(Vv[3][nt], Vv[2][nt]), pk2(Vv[1][nt], Vv[0][nt])}; }
;             *(v2u*)(img + RCH_APT + nt * 512 + laneD * 8) = pa; *(v2u*)(img + RCH_KPT + nt * 512 + laneD * 8) = pk; *(v2u*)(img + RCH_VM + nt * 512 + laneD * 8) = pv;
;             if (fq == 0) *(float*)(img + RCH_GC + (16 * nt + fr) * 4) = tot;
	ds_write_b16 v94, v54
	v_mul_f32_e32 v54, v84, v74
	v_cvt_pk_bf16_f32 v54, v54, s0
	v_mov_b32_e32 v92, v81
	ds_write_b16 v94, v54 offset:2176
	v_cvt_pk_bf16_f32 v54, v69, s0
	v_pk_mul_f32 v[80:81], v[76:77], v[92:93]
	ds_write_b16 v94, v54 offset:6528
	v_cvt_pk_bf16_f32 v54, v80, s0
	ds_write_b16 v94, v54 offset:4352
	v_mul_f32_e64 v54, v74, -v57
	v_cvt_pk_bf16_f32 v74, v54, s0
	s_movk_i32 s0, 0x44
	s_addc_u32 s5, s1, 0
	v_mad_u64_u32 v[152:153], s[0:1], v56, s0, v[0:1]
	v_lshl_add_u32 v54, v152, 1, s25
	ds_write_b16 v54, v74
	v_mul_f32_e32 v74, v36, v78
	v_cvt_pk_bf16_f32 v74, v74, s0
	v_mul_f32_e32 v95, v58, v93
	v_pk_mul_f32 v[92:93], v[68:69], v[80:81] op_sel_hi:[0,1]
	ds_write_b16 v54, v74 offset:2176
	v_cvt_pk_bf16_f32 v74, v81, s0
	v_rcp_f32_e32 v80, v96
	v_rcp_f32_e32 v81, v119
	v_mov_b32_e32 v94, v69
	v_pk_mul_f32 v[114:115], v[68:69], v[94:95] op_sel_hi:[0,1]
	ds_write_b16 v54, v74 offset:4352
	v_cvt_pk_bf16_f32 v74, v95, s0
	v_pk_mul_f32 v[94:95], v[72:73], v[80:81]
	v_pk_mul_f32 v[80:81], v[62:63], v[80:81]
	v_pk_mul_f32 v[152:153], v[68:69], v[94:95] op_sel_hi:[0,1]
	v_pk_mul_f32 v[154:155], v[68:69], v[80:81] op_sel_hi:[0,1]
	v_cvt_pk_bf16_f32 v69, v80, s0
	ds_write_b16 v54, v74 offset:6528
	v_mul_f32_e64 v74, v78, -v39
	ds_write_b16 v54, v69 offset:6664
	v_mul_f32_e64 v69, v96, -v31
	v_cvt_pk_bf16_f32 v74, v74, s0
	v_cvt_pk_bf16_f32 v69, v69, s0
	ds_write_b16 v54, v74 offset:136
	v_mul_f32_e32 v74, v42, v96
	ds_write_b16 v54, v69 offset:272
	v_mul_f32_e32 v69, v44, v119
	v_cvt_pk_bf16_f32 v74, v74, s0
	v_cvt_pk_bf16_f32 v69, v69, s0
	ds_write_b16 v54, v74 offset:2312
	v_cvt_pk_bf16_f32 v74, v94, s0
	ds_write_b16 v54, v69 offset:2448
	v_cvt_pk_bf16_f32 v69, v95, s0
	v_cvt_pk_bf16_f32 v94, v114, v115
	v_add_co_u32_e32 v114, vcc, 0x2000, v2
	ds_write_b16 v54, v69 offset:4624
	v_cvt_pk_bf16_f32 v69, v81, s0
	v_cvt_pk_bf16_f32 v92, v92, v93
	v_cvt_pk_bf16_f32 v93, v152, v153
	v_addc_co_u32_e32 v115, vcc, 0, v3, vcc
	ds_write_b16 v54, v74 offset:4488
	ds_write_b16 v54, v69 offset:6800
	v_cvt_pk_bf16_f32 v95, v154, v155
	global_store_dwordx2 v[114:115], v[92:93], off
	global_store_dwordx2 v[114:115], v[94:95], off offset:2048
	v_add_co_u32_e32 v92, vcc, 0x1000, v2
	v_cmp_gt_u32_e64 s[44:45], 16, v182
	v_cvt_pk_bf16_f32 v80, v82, v34
	v_cvt_pk_bf16_f32 v81, v40, v48
	v_addc_co_u32_e32 v93, vcc, 0, v3, vcc
	global_store_dwordx2 v[92:93], v[80:81], off offset:2048
	s_and_saveexec_b64 s[0:1], s[44:45]
	s_cbranch_execz .LBB0_836
	global_store_dword v61, v68, s[4:5]
.LBB0_836:
	s_or_b64 exec, exec, s[0:1]
	v_add_f32_e32 v68, v141, v125
	v_mul_f32_e64 v69, |v68|, s16
	v_exp_f32_e32 v69, v69
	s_mov_b64 s[0:1], 0x2000
	v_lshl_add_u64 v[80:81], v[2:3], 0, s[0:1]
	s_mov_b64 s[0:1], 0x2800
	v_add_f32_e32 v69, 1.0, v69
	v_lshl_add_u64 v[92:93], v[2:3], 0, s[0:1]
	s_mov_b32 s0, 0x3f317217
	v_log_f32_e32 v69, v69
	s_mov_b32 s1, 0x7f800000
	v_max_f32_e64 v68, -v68, 0
	v_mul_f32_e32 v78, 0x3f317217, v69
	v_fma_f32 v78, v69, s0, -v78
	v_fmac_f32_e32 v78, 0x3377d1cf, v69
	v_fmac_f32_e32 v78, 0x3f317217, v69
	v_add_f32_e32 v114, v138, v125
	v_mul_f32_e64 v115, |v114|, s16
	v_mov_b32_e32 v69, v78
	v_add_f32_e32 v68, v68, v69
	v_add_f32_e32 v69, v140, v125
	v_mul_f32_e64 v74, |v69|, s16
	v_exp_f32_e32 v74, v74
	v_max_f32_e64 v69, -v69, 0
	v_exp_f32_e32 v115, v115
	v_sub_f32_e32 v68, -0.5, v68
	v_add_f32_e32 v74, 1.0, v74
	v_mul_f32_e32 v68, 0x3fb8aa3b, v68
	v_exp_f32_e32 v68, v68
	v_log_f32_e32 v74, v74
	v_mul_f32_e32 v68, 0xbfb8aa3b, v68
	v_exp_f32_e32 v68, v68
	v_mul_f32_e32 v122, v75, v151
	v_mul_f32_e32 v78, 0x3f317217, v74
	v_fma_f32 v78, v74, s0, -v78
	v_fmac_f32_e32 v78, 0x3377d1cf, v74
	v_fmac_f32_e32 v78, 0x3f317217, v74
	v_mul_f32_e32 v75, v127, v122
	v_mul_f32_e32 v127, v97, v145
	v_mov_b32_e32 v74, v78
	v_add_f32_e32 v69, v69, v74
	v_add_f32_e32 v74, v139, v125
	v_mul_f32_e64 v78, |v74|, s16
	v_exp_f32_e32 v78, v78
	v_max_f32_e64 v74, -v74, 0
	v_sub_f32_e32 v69, -0.5, v69
	v_mul_f32_e32 v69, 0x3fb8aa3b, v69
	v_add_f32_e32 v78, 1.0, v78
	v_exp_f32_e32 v69, v69
	v_mul_f32_e32 v125, v71, v87
	v_log_f32_e32 v78, v78
	v_mul_f32_e32 v69, 0xbfb8aa3b, v69
	v_exp_f32_e32 v69, v69
	v_add_u32_e32 v70, v0, v70
	v_mul_f32_e32 v96, 0x3f317217, v78
	v_fma_f32 v96, v78, s0, -v96
	v_fmac_f32_e32 v96, 0x3377d1cf, v78
	v_fmac_f32_e32 v96, 0x3f317217, v78
	v_lshl_add_u32 v138, v70, 1, s25
	s_mov_b64 s[8:9], 0x1800
	v_mov_b32_e32 v78, v96
	v_add_f32_e32 v74, v74, v78
	v_add_f32_e32 v78, 1.0, v115
	v_sub_f32_e32 v74, -0.5, v74
	v_mul_f32_e32 v74, 0x3fb8aa3b, v74
	v_log_f32_e32 v78, v78
	v_max_f32_e64 v96, -v114, 0
	v_exp_f32_e32 v74, v74
	v_lshl_add_u64 v[94:95], v[2:3], 0, s[8:9]
	v_mul_f32_e32 v114, 0x3f317217, v78
	v_fma_f32 v114, v78, s0, -v114
	v_fmac_f32_e32 v114, 0x3377d1cf, v78
	v_fmac_f32_e32 v114, 0x3f317217, v78
	v_mul_f32_e32 v71, 0xbfb8aa3b, v74
	v_exp_f32_e32 v71, v71
	v_mov_b32_e32 v78, v114
	v_add_f32_e32 v78, v96, v78
	v_sub_f32_e32 v78, -0.5, v78
	v_mul_f32_e32 v78, 0x3fb8aa3b, v78
	v_exp_f32_e32 v78, v78
	s_nop 0
	v_mul_f32_e32 v74, 0xbfb8aa3b, v78
	v_exp_f32_e32 v96, v74
	v_mul_f32_e32 v74, v126, v125
	v_mul_f32_e32 v126, v79, v147
	v_mul_f32_e32 v79, v32, v126
	v_mul_f32_e32 v71, v96, v71
	v_mul_f32_e32 v69, v69, v71
	v_mul_f32_e32 v68, v68, v69
	ds_bpermute_b32 v32, v143, v68
	ds_bpermute_b32 v114, v144, v68
	ds_bpermute_b32 v97, v142, v68
	ds_bpermute_b32 v115, v67, v68
	v_mul_f32_e32 v78, v150, v127
	s_waitcnt lgkmcnt(3)
	v_cndmask_b32_e64 v32, 1.0, v32, s[46:47]
	s_waitcnt lgkmcnt(2)
	v_cndmask_b32_e64 v114, 1.0, v114, s[48:49]
	v_mul_f32_e32 v32, v32, v114
	s_waitcnt lgkmcnt(1)
	v_cndmask_b32_e64 v97, 1.0, v97, s[50:51]
	v_mul_f32_e32 v114, v32, v97
	s_waitcnt lgkmcnt(0)
; __device__ __forceinline__ unsigned pk2(float lo, float hi) { const bf16x2_t r = __builtin_convertvector((f32x2){lo, hi}, bf16x2_t); return __builtin_bit_cast(unsigned, r); }
; __device__ __forceinline__ float softplusf_(float x) { return fmaxf(x, 0.f) + __logf(1.f + __expf(-fabsf(x))); }
; __device__ __forceinline__ void rwkv_prep_item(KArgs a, int l, int item, LAS unsigned char* lds, int tid, int lane, int wave) {
;     ...
;         const float rn = rsqrtf(row16_sum(ss) + 1e-12f);
;         float bon = 0.f;
; #pragma unroll
;         for (int nt = 0; nt < 4; ++nt) { const int c = 64 * wave + 16 * nt + fr;
;             Wd[0][i][nt] = __expf(-__expf(-softplusf_(-(w0f[nt] + acc[0][nt][i])) - 0.5f)); Wd[1][i][nt] = __expf(-__expf(-softplusf_(-(w0b[nt] + acc[1][nt][i])) - 0.5f));
;             const float kk = kkv[nt] * rn; Km[i][nt] = k[nt] * (1.f + (av[nt] - 1.f) * kac[nt]); Ka[i][nt] = kk * av[nt]; Nn[i][nt] = -kk;
;     ...
;             float tot = G * __int_as_float(__builtin_amdgcn_ds_bpermute((lane ^ 16) << 2, __float_as_int(G)));
;             tot = tot * __int_as_float(__builtin_amdgcn_ds_bpermute((lane ^ 32) << 2, __float_as_int(tot)));
;             float ap[4], kp[4];
; #pragma unroll
;             for (int i = 0; i < 4; ++i) { const int td = d ? 15 - (4 * fq + i) : 4 * fq + i; const float ig = __builtin_amdgcn_rcpf(gam[i]);
;                 const float at_ = Ka[i][nt] * ig, kt_ = Km[i][nt] * ig; ap[i] = at_ * tot; kp[i] = kt_ * tot;
;                 NTl[td * 68 + 16 * nt + fr] = bf1(gpv[i] * Nn[i][nt]); RTl[td * 68 + 16 * nt + fr] = bf1(gam[i] * Rr[i][nt]);
;                 ATl[td * 68 + 16 * nt + fr] = bf1(at_); KTl[td * 68 + 16 * nt + fr] = bf1(kt_); }
;             v2u pa, pk, pv;
;             if (d == 0) { pa = (v2u){pk2(ap[0], ap[1]), pk2(ap[2], ap[3])}; pk = (v2u){pk2(kp[0], kp[1]), pk2(kp[2], kp[3])}; pv = (v2u){pk2(Vv[0][nt], Vv[1][nt]), pk2(Vv[2][nt], Vv[3][nt])}; }
;             else { pa = (v2u){pk2(ap[3], ap[2]), pk2(ap[1], ap[0])}; pk = (v2u){pk2(kp[3], kp[2]), pk2(kp[1], kp[0])}; pv = (v2u){pk2(Vv[3][nt], Vv[2][nt]), pk2(Vv[1][nt], Vv[0][nt])}; }
;             *(v2u*)(img + RCH_APT + nt * 512 + laneD * 8) = pa; *(v2u*)(img + RCH_KPT + nt * 512 + laneD * 8) = pk; *(v2u*)(img + RCH_VM + nt * 512 + laneD * 8) = pv;
;             if (fq == 0) *(float*)(img + RCH_GC + (16 * nt + fr) * 4) = tot;
	v_mul_f32_e32 v32, v68, v115
	v_mul_f32_e32 v119, v96, v114
	ds_bpermute_b32 v96, v7, v32
	v_rcp_f32_e32 v97, v119
	v_mul_f32_e32 v139, v71, v114
	v_mul_f32_e32 v150, v69, v114
	v_mul_f32_e32 v156, v68, v114
	s_waitcnt lgkmcnt(0)
	v_pk_mul_f32 v[68:69], v[32:33], v[96:97]
	v_mul_f32_e64 v32, v114, -v127
	v_rcp_f32_e32 v71, v139
	v_cvt_pk_bf16_f32 v32, v32, s0
	ds_write_b16 v138, v32 offset:32
	v_mul_f32_e32 v32, v85, v119
	v_cvt_pk_bf16_f32 v32, v32, s0
	v_mov_b32_e32 v70, v97
	ds_write_b16 v138, v32 offset:2208
	v_cvt_pk_bf16_f32 v32, v69, s0
	v_mul_f32_e32 v115, v38, v71
	v_pk_mul_f32 v[70:71], v[78:79], v[70:71]
	ds_write_b16 v138, v32 offset:6560
	v_cvt_pk_bf16_f32 v32, v70, s0
	ds_write_b16 v138, v32 offset:4384
	v_mul_f32_e64 v32, v119, -v126
	v_cvt_pk_bf16_f32 v32, v32, s0
	ds_write_b16 v54, v32 offset:32
	v_mul_f32_e32 v32, v37, v139
	v_cvt_pk_bf16_f32 v32, v32, s0
	ds_write_b16 v54, v32 offset:2208
	v_cvt_pk_bf16_f32 v32, v71, s0
	v_pk_mul_f32 v[96:97], v[68:69], v[70:71] op_sel_hi:[0,1]
	ds_write_b16 v54, v32 offset:4384
	v_cvt_pk_bf16_f32 v32, v115, s0
	v_rcp_f32_e32 v70, v150
	v_rcp_f32_e32 v71, v156
	ds_write_b16 v54, v32 offset:6560
	v_mul_f32_e64 v32, v139, -v125
	v_cvt_pk_bf16_f32 v32, v32, s0
	v_mov_b32_e32 v114, v69
	ds_write_b16 v54, v32 offset:168
	v_mul_f32_e32 v32, v43, v150
	v_pk_mul_f32 v[140:141], v[68:69], v[114:115] op_sel_hi:[0,1]
	v_cvt_pk_bf16_f32 v32, v32, s0
	v_pk_mul_f32 v[114:115], v[74:75], v[70:71]
	ds_write_b16 v54, v32 offset:2344
	v_cvt_pk_bf16_f32 v32, v114, s0
	v_pk_mul_f32 v[70:71], v[16:17], v[70:71]
	ds_write_b16 v54, v32 offset:4520
	v_cvt_pk_bf16_f32 v32, v70, s0
	ds_write_b16 v54, v32 offset:6696
	v_mul_f32_e64 v32, v150, -v122
	v_cvt_pk_bf16_f32 v32, v32, s0
	ds_write_b16 v54, v32 offset:304
	v_mul_f32_e32 v32, v45, v156
	v_cvt_pk_bf16_f32 v32, v32, s0
	v_pk_mul_f32 v[152:153], v[68:69], v[114:115] op_sel_hi:[0,1]
	ds_write_b16 v54, v32 offset:2480
	v_cvt_pk_bf16_f32 v32, v115, s0
	v_pk_mul_f32 v[154:155], v[68:69], v[70:71] op_sel_hi:[0,1]
	ds_write_b16 v54, v32 offset:4656
	v_cvt_pk_bf16_f32 v32, v71, s0
	v_cvt_pk_bf16_f32 v96, v96, v97
	v_cvt_pk_bf16_f32 v97, v152, v153
	ds_write_b16 v54, v32 offset:6832
	v_cvt_pk_bf16_f32 v70, v83, v35
	v_cvt_pk_bf16_f32 v71, v41, v49
	v_cvt_pk_bf16_f32 v114, v140, v141
	v_cvt_pk_bf16_f32 v115, v154, v155
	global_store_dwordx2 v[80:81], v[96:97], off offset:512
	global_store_dwordx2 v[92:93], v[114:115], off offset:512
	global_store_dwordx2 v[94:95], v[70:71], off offset:512
	s_and_saveexec_b64 s[0:1], s[44:45]
	s_cbranch_execz .LBB0_838
	global_store_dword v61, v68, s[4:5] offset:64
.LBB0_838:
	s_or_b64 exec, exec, s[0:1]
	v_add_f32_e32 v32, v137, v129
	v_mul_f32_e64 v68, |v32|, s16
	v_exp_f32_e32 v68, v68
	s_mov_b32 s0, 0x3f317217
	s_mov_b32 s1, 0x7f800000
	v_add_f32_e32 v70, v136, v129
	v_add_f32_e32 v68, 1.0, v68
	v_max_f32_e64 v32, -v32, 0
	v_mul_f32_e32 v114, v52, v151
	v_log_f32_e32 v68, v68
	v_mul_f32_e64 v69, |v70|, s16
	v_max_f32_e64 v52, -v70, 0
	v_mul_f32_e32 v96, 0x3f317217, v68
	v_fma_f32 v96, v68, s0, -v96
	v_fmac_f32_e32 v96, 0x3377d1cf, v68
	v_fmac_f32_e32 v96, 0x3f317217, v68
	v_mul_f32_e32 v115, v90, v87
	v_mul_f32_e32 v119, v88, v145
	v_mov_b32_e32 v68, v96
	v_add_f32_e32 v32, v32, v68
	v_exp_f32_e32 v68, v69
	v_add_f32_e32 v96, v134, v129
	v_mul_f32_e64 v97, |v96|, s16
	v_exp_f32_e32 v97, v97
	v_add_f32_e32 v68, 1.0, v68
	v_sub_f32_e32 v32, -0.5, v32
	v_mul_f32_e32 v32, 0x3fb8aa3b, v32
	v_log_f32_e32 v68, v68
	v_exp_f32_e32 v32, v32
	v_mul_f32_e32 v69, v118, v114
	v_mul_f32_e32 v118, v64, v147
	v_mul_f32_e32 v70, 0x3f317217, v68
	v_fma_f32 v70, v68, s0, -v70
	v_fmac_f32_e32 v70, 0x3377d1cf, v68
	v_fmac_f32_e32 v70, 0x3f317217, v68
	v_mul_f32_e32 v32, 0xbfb8aa3b, v32
	v_exp_f32_e32 v32, v32
	v_mov_b32_e32 v68, v70
	v_add_f32_e32 v52, v52, v68
	v_add_f32_e32 v68, v135, v129
	v_mul_f32_e64 v70, |v68|, s16
	v_exp_f32_e32 v70, v70
	v_max_f32_e64 v68, -v68, 0
	v_sub_f32_e32 v52, -0.5, v52
	v_mul_f32_e32 v52, 0x3fb8aa3b, v52
	v_add_f32_e32 v70, 1.0, v70
	v_exp_f32_e32 v52, v52
	s_nop 0
	v_log_f32_e32 v70, v70
	v_mul_f32_e32 v52, 0xbfb8aa3b, v52
	v_exp_f32_e32 v52, v52
	v_mul_f32_e32 v71, 0x3f317217, v70
	v_fma_f32 v71, v70, s0, -v71
	v_fmac_f32_e32 v71, 0x3377d1cf, v70
	v_fmac_f32_e32 v71, 0x3f317217, v70
	s_nop 1
	v_mov_b32_e32 v70, v71
	v_add_f32_e32 v68, v68, v70
	v_add_f32_e32 v70, 1.0, v97
	v_sub_f32_e32 v68, -0.5, v68
	v_mul_f32_e32 v68, 0x3fb8aa3b, v68
	v_log_f32_e32 v70, v70
	v_max_f32_e64 v71, -v96, 0
	v_exp_f32_e32 v68, v68
	v_mul_f32_e32 v96, 0x3f317217, v70
	v_fma_f32 v96, v70, s0, -v96
	v_fmac_f32_e32 v96, 0x3377d1cf, v70
	v_fmac_f32_e32 v96, 0x3f317217, v70
	v_mul_f32_e32 v68, 0xbfb8aa3b, v68
	v_exp_f32_e32 v90, v68
	v_mov_b32_e32 v70, v96
	v_add_f32_e32 v70, v71, v70
	v_sub_f32_e32 v70, -0.5, v70
	v_mul_f32_e32 v70, 0x3fb8aa3b, v70
	v_exp_f32_e32 v70, v70
	v_mul_f32_e32 v71, v28, v118
	v_mul_f32_e32 v68, 0xbfb8aa3b, v70
	v_exp_f32_e32 v96, v68
	v_mul_f32_e32 v70, v146, v119
	v_mul_f32_e32 v68, v149, v115
	v_mul_f32_e32 v64, v96, v90
	v_mul_f32_e32 v52, v52, v64
	v_mul_f32_e32 v32, v32, v52
	ds_bpermute_b32 v28, v143, v32
	ds_bpermute_b32 v90, v144, v32
	ds_bpermute_b32 v88, v142, v32
	ds_bpermute_b32 v97, v67, v32
	s_waitcnt lgkmcnt(3)
	v_cndmask_b32_e64 v28, 1.0, v28, s[46:47]
	s_waitcnt lgkmcnt(2)
	v_cndmask_b32_e64 v90, 1.0, v90, s[48:49]
	v_mul_f32_e32 v28, v28, v90
	s_waitcnt lgkmcnt(1)
	v_cndmask_b32_e64 v88, 1.0, v88, s[50:51]
	v_mul_f32_e32 v88, v28, v88
	s_waitcnt lgkmcnt(0)
	v_mul_f32_e32 v28, v32, v97
	v_mul_f32_e32 v90, v96, v88
	ds_bpermute_b32 v134, v7, v28
	v_rcp_f32_e32 v135, v90
	v_mul_f32_e32 v64, v64, v88
	v_rcp_f32_e32 v137, v64
	v_mul_f32_e32 v52, v52, v88
	s_waitcnt lgkmcnt(0)
; __device__ __forceinline__ unsigned pk2(float lo, float hi) { const bf16x2_t r = __builtin_convertvector((f32x2){lo, hi}, bf16x2_t); return __builtin_bit_cast(unsigned, r); }
; __device__ __forceinline__ float softplusf_(float x) { return fmaxf(x, 0.f) + __logf(1.f + __expf(-fabsf(x))); }
; __device__ __forceinline__ void rwkv_prep_item(KArgs a, int l, int item, LAS unsigned char* lds, int tid, int lane, int wave) {
;     ...
;         const float rn = rsqrtf(row16_sum(ss) + 1e-12f);
;         float bon = 0.f;
; #pragma unroll
;         for (int nt = 0; nt < 4; ++nt) { const int c = 64 * wave + 16 * nt + fr;
;             Wd[0][i][nt] = __expf(-__expf(-softplusf_(-(w0f[nt] + acc[0][nt][i])) - 0.5f)); Wd[1][i][nt] = __expf(-__expf(-softplusf_(-(w0b[nt] + acc[1][nt][i])) - 0.5f));
;             const float kk = kkv[nt] * rn; Km[i][nt] = k[nt] * (1.f + (av[nt] - 1.f) * kac[nt]); Ka[i][nt] = kk * av[nt]; Nn[i][nt] = -kk;
;     ...
;             float tot = G * __int_as_float(__builtin_amdgcn_ds_bpermute((lane ^ 16) << 2, __float_as_int(G)));
;             tot = tot * __int_as_float(__builtin_amdgcn_ds_bpermute((lane ^ 32) << 2, __float_as_int(tot)));
;             float ap[4], kp[4];
; #pragma unroll
;             for (int i = 0; i < 4; ++i) { const int td = d ? 15 - (4 * fq + i) : 4 * fq + i; const float ig = __builtin_amdgcn_rcpf(gam[i]);
;                 const float at_ = Ka[i][nt] * ig, kt_ = Km[i][nt] * ig; ap[i] = at_ * tot; kp[i] = kt_ * tot;
;                 NTl[td * 68 + 16 * nt + fr] = bf1(gpv[i] * Nn[i][nt]); RTl[td * 68 + 16 * nt + fr] = bf1(gam[i] * Rr[i][nt]);
;                 ATl[td * 68 + 16 * nt + fr] = bf1(at_); KTl[td * 68 + 16 * nt + fr] = bf1(kt_); }
;             v2u pa, pk, pv;
;             if (d == 0) { pa = (v2u){pk2(ap[0], ap[1]), pk2(ap[2], ap[3])}; pk = (v2u){pk2(kp[0], kp[1]), pk2(kp[2], kp[3])}; pv = (v2u){pk2(Vv[0][nt], Vv[1][nt]), pk2(Vv[2][nt], Vv[3][nt])}; }
;             else { pa = (v2u){pk2(ap[3], ap[2]), pk2(ap[1], ap[0])}; pk = (v2u){pk2(kp[3], kp[2]), pk2(kp[1], kp[0])}; pv = (v2u){pk2(Vv[3][nt], Vv[2][nt]), pk2(Vv[1][nt], Vv[0][nt])}; }
;             *(v2u*)(img + RCH_APT + nt * 512 + laneD * 8) = pa; *(v2u*)(img + RCH_KPT + nt * 512 + laneD * 8) = pk; *(v2u*)(img + RCH_VM + nt * 512 + laneD * 8) = pv;
;             if (fq == 0) *(float*)(img + RCH_GC + (16 * nt + fr) * 4) = tot;
	v_pk_mul_f32 v[96:97], v[28:29], v[134:135]
	v_mul_f32_e64 v28, v88, -v119
	v_cvt_pk_bf16_f32 v28, v28, s0
	ds_write_b16 v138, v28 offset:64
	v_mul_f32_e32 v28, v50, v90
	v_cvt_pk_bf16_f32 v28, v28, s0
	v_mov_b32_e32 v136, v135
	ds_write_b16 v138, v28 offset:2240
	v_cvt_pk_bf16_f32 v28, v97, s0
	v_pk_mul_f32 v[134:135], v[70:71], v[136:137]
	ds_write_b16 v138, v28 offset:6592
	v_cvt_pk_bf16_f32 v28, v134, s0
	ds_write_b16 v138, v28 offset:4416
	v_mul_f32_e64 v28, v90, -v118
	v_cvt_pk_bf16_f32 v28, v28, s0
	ds_write_b16 v54, v28 offset:64
	v_mul_f32_e32 v28, v20, v64
	v_cvt_pk_bf16_f32 v28, v28, s0
	v_mul_f32_e32 v32, v32, v88
	v_mul_f32_e32 v141, v30, v137
	ds_write_b16 v54, v28 offset:2240
	v_cvt_pk_bf16_f32 v28, v135, s0
	v_pk_mul_f32 v[136:137], v[96:97], v[134:135] op_sel_hi:[0,1]
	ds_write_b16 v54, v28 offset:4416
	v_cvt_pk_bf16_f32 v28, v141, s0
	v_rcp_f32_e32 v134, v52
	v_rcp_f32_e32 v135, v32
	ds_write_b16 v54, v28 offset:6592
	v_mul_f32_e64 v28, v64, -v115
	v_cvt_pk_bf16_f32 v28, v28, s0
	v_mov_b32_e32 v140, v97
	ds_write_b16 v54, v28 offset:200
	v_mul_f32_e32 v28, v10, v52
	v_pk_mul_f32 v[152:153], v[96:97], v[140:141] op_sel_hi:[0,1]
	v_cvt_pk_bf16_f32 v28, v28, s0
	v_pk_mul_f32 v[140:141], v[68:69], v[134:135]
	ds_write_b16 v54, v28 offset:2376
	v_cvt_pk_bf16_f32 v28, v140, s0
	v_pk_mul_f32 v[134:135], v[12:13], v[134:135]
	ds_write_b16 v54, v28 offset:4552
	v_cvt_pk_bf16_f32 v28, v134, s0
	ds_write_b16 v54, v28 offset:6728
	v_mul_f32_e64 v28, v52, -v114
	v_cvt_pk_bf16_f32 v28, v28, s0
	ds_write_b16 v54, v28 offset:336
	v_mul_f32_e32 v28, v24, v32
	v_cvt_pk_bf16_f32 v28, v28, s0
	v_pk_mul_f32 v[154:155], v[96:97], v[140:141] op_sel_hi:[0,1]
	ds_write_b16 v54, v28 offset:2512
	v_cvt_pk_bf16_f32 v28, v141, s0
	v_pk_mul_f32 v[156:157], v[96:97], v[134:135] op_sel_hi:[0,1]
	ds_write_b16 v54, v28 offset:4688
	v_cvt_pk_bf16_f32 v28, v135, s0
	v_cvt_pk_bf16_f32 v136, v136, v137
	v_cvt_pk_bf16_f32 v137, v154, v155
	ds_write_b16 v54, v28 offset:6864
	v_cvt_pk_bf16_f32 v134, v46, v22
	v_cvt_pk_bf16_f32 v135, v14, v26
	v_cvt_pk_bf16_f32 v140, v152, v153
	v_cvt_pk_bf16_f32 v141, v156, v157
	global_store_dwordx2 v[80:81], v[136:137], off offset:1024
	global_store_dwordx2 v[92:93], v[140:141], off offset:1024
	global_store_dwordx2 v[94:95], v[134:135], off offset:1024
	s_and_saveexec_b64 s[0:1], s[44:45]
	s_cbranch_execz .LBB0_840
	global_store_dword v61, v96, s[4:5] offset:128
.LBB0_840:
	s_or_b64 exec, exec, s[0:1]
	v_add_f32_e32 v28, v133, v123
	v_max_f32_e64 v32, -v28, 0
	v_mul_f32_e64 v28, |v28|, s16
	v_exp_f32_e32 v28, v28
	s_mov_b32 s0, 0x3f317217
	s_mov_b32 s1, 0x7f800000
	v_mul_f32_e32 v87, v91, v87
	v_add_f32_e32 v28, 1.0, v28
	s_nop 1
	v_log_f32_e32 v28, v28
	s_nop 0
	v_mul_f32_e32 v52, 0x3f317217, v28
	v_fma_f32 v52, v28, s0, -v52
	v_fmac_f32_e32 v52, 0x3377d1cf, v28
	v_fmac_f32_e32 v52, 0x3f317217, v28
	s_nop 1
	v_mov_b32_e32 v28, v52
	v_add_f32_e32 v52, v132, v123
	v_max_f32_e64 v64, -v52, 0
	v_mul_f32_e64 v52, |v52|, s16
	v_exp_f32_e32 v52, v52
	v_add_f32_e32 v28, v32, v28
	v_sub_f32_e32 v28, -0.5, v28
	v_mul_f32_e32 v28, 0x3fb8aa3b, v28
	v_add_f32_e32 v52, 1.0, v52
	v_exp_f32_e32 v28, v28
	v_mul_f32_e32 v32, v53, v151
	v_log_f32_e32 v52, v52
	v_mul_f32_e32 v28, 0xbfb8aa3b, v28
	v_exp_f32_e32 v28, v28
	v_mul_f32_e32 v53, v148, v32
	v_mul_f32_e32 v88, 0x3f317217, v52
	v_fma_f32 v88, v52, s0, -v88
	v_fmac_f32_e32 v88, 0x3377d1cf, v52
	v_fmac_f32_e32 v88, 0x3f317217, v52
	s_nop 1
	v_mov_b32_e32 v52, v88
	v_add_f32_e32 v52, v64, v52
	v_add_f32_e32 v64, v131, v123
	v_max_f32_e64 v90, -v64, 0
	v_mul_f32_e64 v64, |v64|, s16
	v_exp_f32_e32 v64, v64
	v_sub_f32_e32 v52, -0.5, v52
	v_mul_f32_e32 v52, 0x3fb8aa3b, v52
	v_exp_f32_e32 v52, v52
	v_add_f32_e32 v64, 1.0, v64
	v_mul_f32_e32 v52, 0xbfb8aa3b, v52
	s_nop 0
	v_log_f32_e32 v64, v64
	v_exp_f32_e32 v88, v52
	v_mul_f32_e32 v52, v128, v87
	v_mul_f32_e32 v91, 0x3f317217, v64
	v_fma_f32 v91, v64, s0, -v91
	v_fmac_f32_e32 v91, 0x3377d1cf, v64
	v_fmac_f32_e32 v91, 0x3f317217, v64
	s_nop 1
	v_mov_b32_e32 v64, v91
	v_add_f32_e32 v64, v90, v64
	v_sub_f32_e32 v64, -0.5, v64
	v_mul_f32_e32 v64, 0x3fb8aa3b, v64
	v_exp_f32_e32 v64, v64
	v_mul_f32_e32 v90, v65, v147
	v_mul_f32_e32 v65, v18, v90
	v_add_f32_e32 v18, v130, v123
	v_mul_f32_e32 v64, 0xbfb8aa3b, v64
	v_exp_f32_e32 v96, v64
	v_max_f32_e64 v64, -v18, 0
	v_mul_f32_e64 v18, |v18|, s16
	v_exp_f32_e32 v18, v18
	s_nop 0
	v_add_f32_e32 v18, 1.0, v18
	s_nop 1
	v_log_f32_e32 v18, v18
	s_nop 0
	v_mul_f32_e32 v91, 0x3f317217, v18
	v_fma_f32 v91, v18, s0, -v91
	v_fmac_f32_e32 v91, 0x3377d1cf, v18
	v_fmac_f32_e32 v91, 0x3f317217, v18
	s_nop 1
	v_mov_b32_e32 v18, v91
	v_add_f32_e32 v18, v64, v18
	v_sub_f32_e32 v18, -0.5, v18
	v_mul_f32_e32 v18, 0x3fb8aa3b, v18
	v_exp_f32_e32 v18, v18
	v_mul_f32_e32 v91, v89, v145
	v_mul_f32_e32 v64, v59, v91
	v_mul_f32_e32 v18, 0xbfb8aa3b, v18
	v_exp_f32_e32 v18, v18
	s_nop 0
	v_mul_f32_e32 v59, v18, v96
	v_mul_f32_e32 v88, v88, v59
	v_mul_f32_e32 v28, v28, v88
	ds_bpermute_b32 v89, v143, v28
	ds_bpermute_b32 v96, v144, v28
	ds_bpermute_b32 v97, v142, v28
	s_waitcnt lgkmcnt(2)
	v_cndmask_b32_e64 v89, 1.0, v89, s[46:47]
	s_waitcnt lgkmcnt(1)
	v_cndmask_b32_e64 v96, 1.0, v96, s[48:49]
	v_mul_f32_e32 v89, v89, v96
	s_waitcnt lgkmcnt(0)
	v_cndmask_b32_e64 v96, 1.0, v97, s[50:51]
	v_mul_f32_e32 v123, v89, v96
	v_mul_f32_e32 v134, v18, v123
	ds_bpermute_b32 v18, v67, v28
	v_rcp_f32_e32 v97, v134
	v_mul_f32_e32 v59, v59, v123
	v_mul_f32_e32 v139, v88, v123
	v_rcp_f32_e32 v129, v59
	s_waitcnt lgkmcnt(0)
	v_mul_f32_e32 v18, v28, v18
	ds_bpermute_b32 v96, v7, v18
	v_mov_b32_e32 v128, v97
	v_mul_f32_e32 v140, v28, v123
	v_mul_f32_e32 v131, v6, v129
	s_waitcnt lgkmcnt(0)
; #define LAS __attribute__((address_space(3)))
; __device__ __forceinline__ void rwkv_prep_item(KArgs a, int l, int item, LAS unsigned char* lds, int tid, int lane, int wave) {
;     ...
;             for (int i = 0; i < 4; ++i) { const int td = d ? 15 - (4 * fq + i) : 4 * fq + i; const float ig = __builtin_amdgcn_rcpf(gam[i]);
;                 const float at_ = Ka[i][nt] * ig, kt_ = Km[i][nt] * ig; ap[i] = at_ * tot; kp[i] = kt_ * tot;
;                 NTl[td * 68 + 16 * nt + fr] = bf1(gpv[i] * Nn[i][nt]); RTl[td * 68 + 16 * nt + fr] = bf1(gam[i] * Rr[i][nt]);
;                 ATl[td * 68 + 16 * nt + fr] = bf1(at_); KTl[td * 68 + 16 * nt + fr] = bf1(kt_); }
;             v2u pa, pk, pv;
;             if (d == 0) { pa = (v2u){pk2(ap[0], ap[1]), pk2(ap[2], ap[3])}; pk = (v2u){pk2(kp[0], kp[1]), pk2(kp[2], kp[3])}; pv = (v2u){pk2(Vv[0][nt], Vv[1][nt]), pk2(Vv[2][nt], Vv[3][nt])}; }
;             else { pa = (v2u){pk2(ap[3], ap[2]), pk2(ap[1], ap[0])}; pk = (v2u){pk2(kp[3], kp[2]), pk2(kp[1], kp[0])}; pv = (v2u){pk2(Vv[3][nt], Vv[2][nt]), pk2(Vv[1][nt], Vv[0][nt])}; }
;             *(v2u*)(img + RCH_APT + nt * 512 + laneD * 8) = pa; *(v2u*)(img + RCH_KPT + nt * 512 + laneD * 8) = pk; *(v2u*)(img + RCH_VM + nt * 512 + laneD * 8) = pv;
;             if (fq == 0) *(float*)(img + RCH_GC + (16 * nt + fr) * 4) = tot;
;         }
;         LDS_WAIT();
; #pragma unroll
;         for (int kt = 0; kt < 4; ++kt) { *(v2u*)(img + RCH_NT + kt * 512 + lane * 8) = *(const LAS v2u*)(NTl + fr * 68 + 16 * kt + 4 * fq); *(v2u*)(img + RCH_RT + kt * 512 + lane * 8) = *(const LAS v2u*)(RTl + fr * 68 + 16 * kt + 4 * fq); }
;         f32x4 cAs = (f32x4){0.f, 0.f, 0.f, 0.f}, cKs = cAs, cAr = cAs, cKr = cAs;
; #pragma unroll
;         for (int sk = 0; sk < 4; ++sk) { const bf16x4 aA = *(const LAS bf16x4*)(ATl + fr * 68 + 16 * sk + 4 * fq), aK = *(const LAS bf16x4*)(KTl + fr * 68 + 16 * sk + 4 * fq);
;             const bf16x4 bN = *(const LAS bf16x4*)(NTl + fr * 68 + 16 * sk + 4 * fq), bR = *(const LAS bf16x4*)(RTl + fr * 68 + 16 * sk + 4 * fq);
;             cAs = __builtin_amdgcn_mfma_f32_16x16x16bf16_1k(aA, bN, cAs, 0, 0, 0); cKs = __builtin_amdgcn_mfma_f32_16x16x16bf16_1k(aK, bN, cKs, 0, 0, 0);
;             cAr = __builtin_amdgcn_mfma_f32_16x16x16bf16_1k(aA, bR, cAr, 0, 0, 0); cKr = __builtin_amdgcn_mfma_f32_16x16x16bf16_1k(aK, bR, cKr, 0, 0, 0); }
	v_pk_mul_f32 v[88:89], v[18:19], v[96:97]
	v_mul_f32_e64 v18, v123, -v91
	v_cvt_pk_bf16_f32 v18, v18, s0
	ds_write_b16 v138, v18 offset:96
	v_mul_f32_e32 v18, v51, v134
	v_cvt_pk_bf16_f32 v18, v18, s0
	ds_write_b16 v138, v18 offset:2272
	v_cvt_pk_bf16_f32 v18, v89, s0
	v_pk_mul_f32 v[96:97], v[64:65], v[128:129]
	ds_write_b16 v138, v18 offset:6624
	v_cvt_pk_bf16_f32 v18, v96, s0
	ds_write_b16 v138, v18 offset:4448
	v_mul_f32_e64 v18, v134, -v90
	v_cvt_pk_bf16_f32 v18, v18, s0
	ds_write_b16 v54, v18 offset:96
	v_mul_f32_e32 v18, v21, v59
	v_cvt_pk_bf16_f32 v18, v18, s0
	ds_write_b16 v54, v18 offset:2272
	v_cvt_pk_bf16_f32 v18, v97, s0
	v_pk_mul_f32 v[128:129], v[88:89], v[96:97] op_sel_hi:[0,1]
	ds_write_b16 v54, v18 offset:4448
	v_cvt_pk_bf16_f32 v18, v131, s0
	v_rcp_f32_e32 v96, v139
	v_rcp_f32_e32 v97, v140
	ds_write_b16 v54, v18 offset:6624
	v_mul_f32_e64 v18, v59, -v87
	v_cvt_pk_bf16_f32 v18, v18, s0
	v_mov_b32_e32 v130, v89
	ds_write_b16 v54, v18 offset:232
	v_mul_f32_e32 v18, v11, v139
	v_pk_mul_f32 v[132:133], v[88:89], v[130:131] op_sel_hi:[0,1]
	v_cvt_pk_bf16_f32 v18, v18, s0
	v_pk_mul_f32 v[130:131], v[52:53], v[96:97]
	ds_write_b16 v54, v18 offset:2408
	v_cvt_pk_bf16_f32 v18, v130, s0
	v_pk_mul_f32 v[96:97], v[8:9], v[96:97]
	ds_write_b16 v54, v18 offset:4584
	v_cvt_pk_bf16_f32 v18, v96, s0
	ds_write_b16 v54, v18 offset:6760
	v_mul_f32_e64 v18, v139, -v32
	v_cvt_pk_bf16_f32 v18, v18, s0
	ds_write_b16 v54, v18 offset:368
	v_mul_f32_e32 v18, v25, v140
	v_cvt_pk_bf16_f32 v18, v18, s0
	v_pk_mul_f32 v[134:135], v[88:89], v[130:131] op_sel_hi:[0,1]
	ds_write_b16 v54, v18 offset:2544
	v_cvt_pk_bf16_f32 v18, v131, s0
	v_pk_mul_f32 v[136:137], v[88:89], v[96:97] op_sel_hi:[0,1]
	ds_write_b16 v54, v18 offset:4720
	v_cvt_pk_bf16_f32 v18, v97, s0
	v_cvt_pk_bf16_f32 v128, v128, v129
	v_cvt_pk_bf16_f32 v129, v134, v135
	ds_write_b16 v54, v18 offset:6896
	v_cvt_pk_bf16_f32 v96, v47, v23
	v_cvt_pk_bf16_f32 v97, v15, v27
	v_cvt_pk_bf16_f32 v130, v132, v133
	v_cvt_pk_bf16_f32 v131, v136, v137
	global_store_dwordx2 v[80:81], v[128:129], off offset:1536
	global_store_dwordx2 v[92:93], v[130:131], off offset:1536
	global_store_dwordx2 v[94:95], v[96:97], off offset:1536
	s_and_saveexec_b64 s[0:1], s[44:45]
	s_cbranch_execz .LBB0_842
	global_store_dword v61, v88, s[4:5] offset:192
.LBB0_842:
	s_or_b64 exec, exec, s[0:1]
	v_add_f32_e32 v18, v113, v121
	v_mul_f32_e64 v54, |v18|, s16
	v_exp_f32_e32 v54, v54
	v_mul_u32_u24_e32 v80, 0x44, v0
	v_lshlrev_b32_e32 v80, 1, v80
	s_mov_b32 s3, 0x3f317217
	v_add_f32_e32 v54, 1.0, v54
	s_mov_b32 s4, 0x7f800000
	v_max_f32_e64 v18, -v18, 0
	v_log_f32_e32 v54, v54
	v_lshlrev_b32_e32 v81, 1, v86
	v_add3_u32 v89, s25, v80, v81
	s_waitcnt lgkmcnt(0)
	v_mul_f32_e32 v80, 0x3f317217, v54
	v_fma_f32 v80, v54, s3, -v80
	v_fmac_f32_e32 v80, 0x3377d1cf, v54
	v_fmac_f32_e32 v80, 0x3f317217, v54
	v_add_u32_e32 v93, 0x1000, v89
	ds_read2_b64 v[128:131], v93 offset0:32 offset1:36
	v_mov_b32_e32 v54, v80
	v_add_f32_e32 v18, v18, v54
	v_add_f32_e32 v54, v112, v121
	v_mul_f32_e64 v80, |v54|, s16
	v_exp_f32_e32 v80, v80
	v_sub_f32_e32 v18, -0.5, v18
	v_mul_f32_e32 v18, 0x3fb8aa3b, v18
	v_exp_f32_e32 v18, v18
	v_add_f32_e32 v80, 1.0, v80
	v_add_u32_e32 v92, 0x1800, v89
	v_mul_f32_e32 v18, 0xbfb8aa3b, v18
	v_log_f32_e32 v80, v80
	v_exp_f32_e32 v95, v18
	v_max_f32_e64 v18, -v54, 0
	v_add_u32_e32 v94, 0x800, v89
	v_mul_f32_e32 v54, 0x3f317217, v80
	v_fma_f32 v54, v80, s3, -v54
	v_fmac_f32_e32 v54, 0x3377d1cf, v80
	v_fmac_f32_e32 v54, 0x3f317217, v80
	ds_read2_b64 v[132:135], v89 offset1:4
	ds_read2_b64 v[136:139], v92 offset0:48 offset1:52
	v_add_f32_e32 v18, v18, v54
	v_add_f32_e32 v54, v111, v121
	v_mul_f32_e64 v80, |v54|, s16
	v_exp_f32_e32 v80, v80
	v_sub_f32_e32 v18, -0.5, v18
	v_mul_f32_e32 v18, 0x3fb8aa3b, v18
	v_exp_f32_e32 v18, v18
	v_add_f32_e32 v80, 1.0, v80
	ds_read2_b64 v[144:147], v94 offset0:16 offset1:20
	v_mul_f32_e32 v18, 0xbfb8aa3b, v18
	v_log_f32_e32 v80, v80
	v_exp_f32_e32 v123, v18
	v_max_f32_e64 v18, -v54, 0
	ds_read2_b64 v[156:159], v93 offset0:40 offset1:44
	v_mul_f32_e32 v54, 0x3f317217, v80
	v_fma_f32 v54, v80, s3, -v54
	v_fmac_f32_e32 v54, 0x3377d1cf, v80
	v_fmac_f32_e32 v54, 0x3f317217, v80
	s_waitcnt lgkmcnt(3)
	v_mfma_f32_16x16x16_bf16 v[140:143], v[128:129], v[132:133], 0
	v_cmp_lt_i32_e64 s[48:49], v60, v0
	v_add_f32_e32 v18, v18, v54
	v_add_f32_e32 v54, v110, v121
	v_mul_f32_e64 v80, |v54|, s16
	v_exp_f32_e32 v80, v80
	s_waitcnt lgkmcnt(1)
	v_mfma_f32_16x16x16_bf16 v[152:155], v[128:129], v[144:145], 0
	v_max_f32_e64 v54, -v54, 0
	v_sub_f32_e32 v18, -0.5, v18
	v_add_f32_e32 v80, 1.0, v80
	v_mfma_f32_16x16x16_bf16 v[148:151], v[136:137], v[132:133], 0
	v_mul_f32_e32 v18, 0x3fb8aa3b, v18
	v_log_f32_e32 v80, v80
	v_mfma_f32_16x16x16_bf16 v[110:113], v[136:137], v[144:145], 0
	v_exp_f32_e32 v18, v18
	v_cmp_lt_i32_e64 s[56:57], v86, v0
	v_mul_f32_e32 v81, 0x3f317217, v80
	v_mfma_f32_16x16x16_bf16 v[140:143], v[130:131], v[134:135], v[140:143]
	v_fma_f32 v81, v80, s3, -v81
	v_fmac_f32_e32 v81, 0x3377d1cf, v80
	v_fmac_f32_e32 v81, 0x3f317217, v80
	v_mfma_f32_16x16x16_bf16 v[128:131], v[130:131], v[146:147], v[152:155]
	s_nop 2
	ds_read2_b64 v[152:155], v89 offset0:8 offset1:12
	ds_read2_b64 v[160:163], v92 offset0:56 offset1:60
	v_mul_f32_e32 v18, 0xbfb8aa3b, v18
	v_mfma_f32_16x16x16_bf16 v[148:151], v[138:139], v[134:135], v[148:151]
	v_mov_b32_e32 v80, v81
	v_mfma_f32_16x16x16_bf16 v[110:113], v[138:139], v[146:147], v[110:113]
	v_add_f32_e32 v54, v54, v80
	v_sub_f32_e32 v54, -0.5, v54
	v_mul_f32_e32 v54, 0x3fb8aa3b, v54
	s_waitcnt lgkmcnt(1)
; __device__ __forceinline__ void rwkv_prep_item(KArgs a, int l, int item, LAS unsigned char* lds, int tid, int lane, int wave) {
;     ...
;         const int cidx = d ? (isctx ? (240 - j0) / 16 : (2544 - j0) / 16) : j0 / 16;
;         unsigned char* img = ws + OFF_RCH + ((size_t)((b * 2 + d) * 8 + h) * 144 + cidx) * RCH_BYTES;
;         const int laneD = d ? ((3 - fq) * 16 + fr) : lane;
; #pragma unroll
;         for (int nt = 0; nt < 4; ++nt) {
;             float gam[4], gpv[4], G, E;
;             if (d == 0) { gam[0] = Wd[0][0][nt]; gam[1] = gam[0] * Wd[0][1][nt]; gam[2] = gam[1] * Wd[0][2][nt]; gam[3] = gam[2] * Wd[0][3][nt]; G = gam[3];
;                 const float g1 = __int_as_float(__builtin_amdgcn_ds_bpermute((lane - 16) << 2, __float_as_int(G))), g2 = __int_as_float(__builtin_amdgcn_ds_bpermute((lane - 32) << 2, __float_as_int(G))), g3 = __int_as_float(__builtin_amdgcn_ds_bpermute((lane - 48) << 2, __float_as_int(G)));
;                 E = (fq >= 1 ? g1 : 1.f) * (fq >= 2 ? g2 : 1.f) * (fq >= 3 ? g3 : 1.f);
;                 gpv[0] = E; gpv[1] = E * gam[0]; gpv[2] = E * gam[1]; gpv[3] = E * gam[2];
;     ...
;         f32x4 cAs = (f32x4){0.f, 0.f, 0.f, 0.f}, cKs = cAs, cAr = cAs, cKr = cAs;
; #pragma unroll
;         for (int sk = 0; sk < 4; ++sk) { const bf16x4 aA = *(const LAS bf16x4*)(ATl + fr * 68 + 16 * sk + 4 * fq), aK = *(const LAS bf16x4*)(KTl + fr * 68 + 16 * sk + 4 * fq);
;             const bf16x4 bN = *(const LAS bf16x4*)(NTl + fr * 68 + 16 * sk + 4 * fq), bR = *(const LAS bf16x4*)(RTl + fr * 68 + 16 * sk + 4 * fq);
;             cAs = __builtin_amdgcn_mfma_f32_16x16x16bf16_1k(aA, bN, cAs, 0, 0, 0); cKs = __builtin_amdgcn_mfma_f32_16x16x16bf16_1k(aK, bN, cKs, 0, 0, 0);
;             cAr = __builtin_amdgcn_mfma_f32_16x16x16bf16_1k(aA, bR, cAr, 0, 0, 0); cKr = __builtin_amdgcn_mfma_f32_16x16x16bf16_1k(aK, bR, cKr, 0, 0, 0); }
; #pragma unroll
;         for (int j = 0; j < 4; ++j) { const int ii = 4 * fq + j; if (!(ii < fr)) { cAs[j] = 0.f; cKs[j] = 0.f; } if (!(ii <= fr)) { cAr[j] = 0.f; cKr[j] = 0.f; } }
;         *(v2u*)(img + RCH_KST + lane * 8) = (v2u){pk2(cKs[0], cKs[1]), pk2(cKs[2], cKs[3])}; *(v2u*)(img + RCH_ART + lane * 8) = (v2u){pk2(cAr[0], cAr[1]), pk2(cAr[2], cAr[3])};
;         *(v2u*)(img + RCH_KRT + lane * 8) = (v2u){pk2(cKr[0], cKr[1]), pk2(cKr[2], cKr[3])};
;         *(LAS f32x4*)(ASl + (d * 16 + fr) * 20 + 4 * fq) = cAs;
	v_mfma_f32_16x16x16_bf16 v[136:139], v[156:157], v[152:153], v[140:143]
	v_exp_f32_e32 v54, v54
	v_cmp_lt_i32_e64 s[46:47], v66, v0
	v_cmp_lt_i32_e32 vcc, v56, v0
	ds_read2_b64 v[140:143], v94 offset0:24 offset1:28
	s_waitcnt lgkmcnt(1)
	v_mfma_f32_16x16x16_bf16 v[148:151], v[160:161], v[152:153], v[148:151]
	s_or_b64 s[48:49], s[46:47], s[48:49]
	v_exp_f32_e32 v121, v18
	v_mul_f32_e32 v18, 0xbfb8aa3b, v54
	s_waitcnt lgkmcnt(0)
	v_mfma_f32_16x16x16_bf16 v[128:131], v[156:157], v[140:141], v[128:131]
	s_or_b64 s[50:51], s[48:49], vcc
	v_exp_f32_e32 v156, v18
	v_mov_b32_e32 v18, s35
	v_mfma_f32_16x16x16_bf16 v[110:113], v[160:161], v[140:141], v[110:113]
	v_mov_b32_e32 v54, s35
	v_cmp_gt_i32_e64 s[60:61], v86, v0
	s_or_b64 s[52:53], s[50:51], s[56:57]
	v_mfma_f32_16x16x16_bf16 v[148:151], v[162:163], v[154:155], v[148:151]
	s_movk_i32 s3, 0x1000
	v_and_b32_e32 v88, -16, v182
	v_cmp_gt_i32_e64 s[58:59], v60, v0
	v_mfma_f32_16x16x16_bf16 v[128:131], v[158:159], v[142:143], v[128:131]
	v_cmp_gt_i32_e64 s[54:55], v66, v0
	s_nop 2
	v_cndmask_b32_e64 v81, 0, v151, s[46:47]
	v_cndmask_b32_e64 v96, 0, v150, s[48:49]
	v_mfma_f32_16x16x16_bf16 v[110:113], v[162:163], v[142:143], v[110:113]
	v_cndmask_b32_e64 v80, 0, v149, s[50:51]
	v_cndmask_b32_e64 v18, v128, v18, s[60:61]
	v_cndmask_b32_e64 v97, 0, v148, s[52:53]
	v_mfma_f32_16x16x16_bf16 v[136:139], v[158:159], v[154:155], v[136:139]
	v_cvt_pk_bf16_f32 v81, v96, v81
	s_nop 2
	v_cndmask_b32_e64 v54, v110, v54, s[60:61]
	v_add_co_u32_e32 v96, vcc, s3, v2
	v_add_u32_e32 v28, s25, v88
	v_cndmask_b32_e64 v18, v18, v128, s[56:57]
	v_cndmask_b32_e64 v128, 0, v129, s[56:57]
	v_cndmask_b32_e64 v54, v54, v110, s[56:57]
	v_cndmask_b32_e64 v110, 0, v111, s[56:57]
	v_cndmask_b32_e64 v111, v130, 0, s[58:59]
	v_cndmask_b32_e64 v129, v131, 0, s[54:55]
	v_cvt_pk_bf16_f32 v80, v97, v80
	v_addc_co_u32_e32 v97, vcc, 0, v3, vcc
	s_movk_i32 s3, 0x50
	global_store_dwordx2 v[2:3], v[132:133], off
	global_store_dwordx2 v[2:3], v[144:145], off offset:2048
	global_store_dwordx2 v[2:3], v[134:135], off offset:512
	global_store_dwordx2 v[2:3], v[146:147], off offset:2560
	global_store_dwordx2 v[2:3], v[152:153], off offset:1024
	global_store_dwordx2 v[2:3], v[140:141], off offset:3072
	global_store_dwordx2 v[2:3], v[154:155], off offset:1536
	global_store_dwordx2 v[2:3], v[142:143], off offset:3584
	v_cndmask_b32_e64 v112, v112, 0, s[58:59]
	v_cndmask_b32_e64 v135, 0, v139, s[46:47]
	v_cndmask_b32_e64 v134, 0, v138, s[48:49]
	v_cndmask_b32_e64 v133, 0, v137, s[50:51]
	v_cndmask_b32_e64 v132, 0, v136, s[52:53]
	v_cndmask_b32_e64 v113, v113, 0, s[54:55]
	global_store_dwordx2 v[96:97], v[80:81], off
	v_cvt_pk_bf16_f32 v80, v18, v128
	v_cvt_pk_bf16_f32 v81, v111, v129
	v_mad_u32_u24 v18, v0, s3, v28
	v_sub_u32_e32 v59, v0, v88
	global_store_dwordx2 v[96:97], v[80:81], off offset:1024
	v_cvt_pk_bf16_f32 v80, v54, v110
	v_cvt_pk_bf16_f32 v81, v112, v113
	ds_write_b128 v18, v[132:135] offset:8704
	v_mov_b32_e32 v18, 0x180
	global_store_dwordx2 v[96:97], v[80:81], off offset:1536
	v_lshl_add_u32 v80, v59, 3, v18
	v_mul_f32_e32 v18, v95, v123
	v_mul_f32_e32 v54, v121, v18
	v_mul_f32_e32 v59, v156, v54
	ds_bpermute_b32 v96, v61, v59 offset:64
	ds_bpermute_b32 v97, v61, v59 offset:128
	ds_bpermute_b32 v110, v61, v59 offset:192
	s_sub_i32 s0, 0x9f0, s6
	s_sub_i32 s1, 0xf0, s6
	ds_bpermute_b32 v111, v67, v59
	s_lshr_b32 s0, s0, 4
	s_ashr_i32 s1, s1, 4
	s_and_b64 s[4:5], s[40:41], exec
	v_cmp_gt_i32_e64 s[40:41], 3, v184
	v_cmp_gt_i32_e64 s[62:63], 2, v184
	s_cselect_b32 s0, s1, s0
	s_add_i32 s1, s2, 8
	s_waitcnt lgkmcnt(3)
	v_cndmask_b32_e64 v96, 1.0, v96, s[40:41]
	s_waitcnt lgkmcnt(2)
	v_cndmask_b32_e64 v97, 1.0, v97, s[62:63]
	v_cmp_gt_i32_e64 s[64:65], 1, v184
	s_mul_hi_i32 s2, s1, 0x90
	s_mulk_i32 s1, 0x90
	s_ashr_i32 s3, s0, 31
	v_mul_f32_e32 v96, v96, v97
	s_waitcnt lgkmcnt(1)
	v_cndmask_b32_e64 v97, 1.0, v110, s[64:65]
	s_add_u32 s0, s1, s0
	v_mul_f32_e32 v121, v96, v97
	s_waitcnt lgkmcnt(0)
	v_mul_f32_e32 v96, v59, v111
	s_addc_u32 s1, s2, s3
	ds_bpermute_b32 v97, v7, v96
	s_mulk_i32 s1, 0x3100
	s_mul_hi_u32 s2, s0, 0x3100
	s_add_i32 s2, s2, s1
	s_mulk_i32 s0, 0x3100
	v_readlane_b32 s4, v254, 41
	v_readlane_b32 s5, v254, 42
	s_add_u32 s68, s4, s0
	v_mul_f32_e32 v123, v54, v121
	s_addc_u32 s69, s5, s2
	v_mul_f32_e32 v54, v59, v121
	v_sub_u32_e32 v59, 15, v86
	v_mul_f32_e64 v86, v123, -v124
	s_movk_i32 s2, 0x44
	v_mul_f32_e32 v128, v18, v121
	s_waitcnt lgkmcnt(0)
	v_mul_f32_e32 v18, v96, v97
	v_cvt_pk_bf16_f32 v96, v86, s0
	v_mad_u64_u32 v[110:111], s[0:1], v59, s2, v[0:1]
	v_lshl_add_u32 v86, v110, 1, s25
	s_waitcnt lgkmcnt(0)
; __device__ __forceinline__ unsigned pk2(float lo, float hi) { const bf16x2_t r = __builtin_convertvector((f32x2){lo, hi}, bf16x2_t); return __builtin_bit_cast(unsigned, r); }
; __device__ __forceinline__ float softplusf_(float x) { return fmaxf(x, 0.f) + __logf(1.f + __expf(-fabsf(x))); }
; __device__ __forceinline__ bf16 bf1(float x) { return (bf16)(pk2(x, x) & 0xffffu); }
; __device__ __forceinline__ void rwkv_prep_item(KArgs a, int l, int item, LAS unsigned char* lds, int tid, int lane, int wave) {
;     ...
;             Wd[0][i][nt] = __expf(-__expf(-softplusf_(-(w0f[nt] + acc[0][nt][i])) - 0.5f)); Wd[1][i][nt] = __expf(-__expf(-softplusf_(-(w0b[nt] + acc[1][nt][i])) - 0.5f));
;     ...
;             float tot = G * __int_as_float(__builtin_amdgcn_ds_bpermute((lane ^ 16) << 2, __float_as_int(G)));
;             tot = tot * __int_as_float(__builtin_amdgcn_ds_bpermute((lane ^ 32) << 2, __float_as_int(tot)));
;             float ap[4], kp[4];
; #pragma unroll
;             for (int i = 0; i < 4; ++i) { const int td = d ? 15 - (4 * fq + i) : 4 * fq + i; const float ig = __builtin_amdgcn_rcpf(gam[i]);
;                 const float at_ = Ka[i][nt] * ig, kt_ = Km[i][nt] * ig; ap[i] = at_ * tot; kp[i] = kt_ * tot;
;                 NTl[td * 68 + 16 * nt + fr] = bf1(gpv[i] * Nn[i][nt]); RTl[td * 68 + 16 * nt + fr] = bf1(gam[i] * Rr[i][nt]);
;                 ATl[td * 68 + 16 * nt + fr] = bf1(at_); KTl[td * 68 + 16 * nt + fr] = bf1(kt_); }
;             v2u pa, pk, pv;
;             if (d == 0) { pa = (v2u){pk2(ap[0], ap[1]), pk2(ap[2], ap[3])}; pk = (v2u){pk2(kp[0], kp[1]), pk2(kp[2], kp[3])}; pv = (v2u){pk2(Vv[0][nt], Vv[1][nt]), pk2(Vv[2][nt], Vv[3][nt])}; }
;             else { pa = (v2u){pk2(ap[3], ap[2]), pk2(ap[1], ap[0])}; pk = (v2u){pk2(kp[3], kp[2]), pk2(kp[1], kp[0])}; pv = (v2u){pk2(Vv[3][nt], Vv[2][nt]), pk2(Vv[1][nt], Vv[0][nt])}; }
;             *(v2u*)(img + RCH_APT + nt * 512 + laneD * 8) = pa; *(v2u*)(img + RCH_KPT + nt * 512 + laneD * 8) = pk; *(v2u*)(img + RCH_VM + nt * 512 + laneD * 8) = pv;
;             if (fq == 0) *(float*)(img + RCH_GC + (16 * nt + fr) * 4) = tot;
	v_rcp_f32_e32 v97, v54
	ds_write_b16 v86, v96
	v_rcp_f32_e32 v96, v123
	v_mul_f32_e32 v54, v84, v54
	v_mov_b32_e32 v110, v77
	v_mov_b32_e32 v111, v76
	v_cvt_pk_bf16_f32 v54, v54, s0
	v_pk_mul_f32 v[110:111], v[110:111], v[96:97]
	ds_write_b16 v86, v54 offset:2176
	v_cvt_pk_bf16_f32 v54, v111, s0
	v_mov_b32_e32 v59, v55
	ds_write_b16 v86, v54 offset:4352
	v_pk_mul_f32 v[54:55], v[58:59], v[96:97]
	v_sub_u32_e32 v56, 15, v56
	v_cvt_pk_bf16_f32 v58, v55, s0
	ds_write_b16 v86, v58 offset:6528
	v_pk_mul_f32 v[58:59], v[18:19], v[54:55] op_sel_hi:[0,1]
	v_mul_f32_e64 v55, v128, -v57
	v_cvt_pk_bf16_f32 v55, v55, s0
	v_mad_u64_u32 v[56:57], s[0:1], v56, s2, v[0:1]
	v_mul_f32_e32 v36, v36, v123
	v_lshl_add_u32 v76, v56, 1, s25
	v_cvt_pk_bf16_f32 v36, v36, s0
	v_mul_f32_e32 v95, v95, v121
	ds_write_b16 v76, v36 offset:2176
	v_cvt_pk_bf16_f32 v36, v110, s0
	ds_write_b16 v76, v55
	ds_write_b16 v76, v36 offset:4352
	v_cvt_pk_bf16_f32 v36, v54, s0
	v_rcp_f32_e32 v55, v128
	v_rcp_f32_e32 v54, v95
	ds_write_b16 v76, v36 offset:6528
	v_sub_u32_e32 v36, 15, v60
	v_mul_f32_e64 v39, v95, -v39
	v_cvt_pk_bf16_f32 v39, v39, s0
	v_mad_u64_u32 v[56:57], s[0:1], v36, s2, v[0:1]
	v_lshl_add_u32 v36, v56, 1, s25
	v_mov_b32_e32 v56, v73
	v_mov_b32_e32 v57, v72
	ds_write_b16 v36, v39
	v_mul_f32_e32 v39, v42, v128
	v_pk_mul_f32 v[56:57], v[56:57], v[54:55]
	v_mov_b32_e32 v96, v63
	v_mov_b32_e32 v97, v62
	v_cvt_pk_bf16_f32 v39, v39, s0
	v_cvt_pk_bf16_f32 v42, v57, s0
	v_pk_mul_f32 v[54:55], v[96:97], v[54:55]
	ds_write_b16 v36, v39 offset:2176
	v_sub_u32_e32 v39, 15, v66
	ds_write_b16 v36, v42 offset:4352
	v_cvt_pk_bf16_f32 v42, v55, s0
	v_mul_f32_e64 v31, v121, -v31
	ds_write_b16 v36, v42 offset:6528
	v_cvt_pk_bf16_f32 v42, v31, s0
	v_mul_lo_u32 v31, v39, s2
	v_or_b32_e32 v39, v31, v0
	v_lshl_add_u32 v39, v39, 1, s25
	v_ashrrev_i32_e32 v81, 31, v80
	ds_write_b16 v39, v42
	v_mul_f32_e32 v42, v44, v95
	v_lshl_add_u64 v[80:81], s[68:69], 0, v[80:81]
	v_pk_mul_f32 v[62:63], v[18:19], v[54:55] op_sel_hi:[0,1]
	v_cvt_pk_bf16_f32 v42, v42, s0
	v_pk_mul_f32 v[112:113], v[18:19], v[110:111] op_sel_hi:[0,1]
	v_pk_mul_f32 v[72:73], v[18:19], v[56:57] op_sel_hi:[0,1]
	ds_write_b16 v39, v42 offset:2176
	v_cvt_pk_bf16_f32 v42, v56, s0
	v_cvt_pk_bf16_f32 v56, v62, v63
	v_add_co_u32_e32 v62, vcc, 0x2000, v80
	ds_write_b16 v39, v42 offset:4352
	v_cvt_pk_bf16_f32 v42, v54, s0
	v_cvt_pk_bf16_f32 v57, v58, v59
	v_cvt_pk_bf16_f32 v58, v72, v73
	v_cvt_pk_bf16_f32 v59, v112, v113
	v_addc_co_u32_e32 v63, vcc, 0, v81, vcc
	s_add_u32 s70, s68, 0x3000
	ds_write_b16 v39, v42 offset:6528
	global_store_dwordx2 v[62:63], v[58:59], off
	global_store_dwordx2 v[62:63], v[56:57], off offset:2048
	v_add_co_u32_e32 v56, vcc, 0x1000, v80
	s_addc_u32 s71, s69, 0
	v_cvt_pk_bf16_f32 v54, v48, v40
	v_cvt_pk_bf16_f32 v55, v34, v82
	v_addc_co_u32_e32 v57, vcc, 0, v81, vcc
	global_store_dwordx2 v[56:57], v[54:55], off offset:2048
	s_and_saveexec_b64 s[0:1], s[44:45]
	s_cbranch_execz .LBB0_844
	global_store_dword v61, v18, s[70:71]
.LBB0_844:
	s_or_b64 exec, exec, s[0:1]
	v_add_f32_e32 v18, v109, v120
	v_mul_f32_e64 v34, |v18|, s16
	v_exp_f32_e32 v39, v34
	s_mov_b32 s0, 0x3f317217
	s_mov_b32 s1, 0x7f800000
	v_max_f32_e64 v18, -v18, 0
	v_add_f32_e32 v39, 1.0, v39
	v_add_f32_e32 v55, v106, v120
	v_mul_f32_e64 v56, |v55|, s16
	v_log_f32_e32 v39, v39
	v_exp_f32_e32 v56, v56
	v_add_u32_e32 v34, 64, v61
	v_mul_f32_e32 v44, 0x3f317217, v39
	v_fma_f32 v44, v39, s0, -v44
	v_fmac_f32_e32 v44, 0x3377d1cf, v39
	v_fmac_f32_e32 v44, 0x3f317217, v39
	v_add_u32_e32 v40, 0x80, v61
	v_mov_b32_e32 v72, v79
	v_mov_b32_e32 v39, v44
	v_add_f32_e32 v18, v18, v39
	v_add_f32_e32 v39, v108, v120
	v_mul_f32_e64 v42, |v39|, s16
	v_exp_f32_e32 v42, v42
	v_max_f32_e64 v39, -v39, 0
	v_sub_f32_e32 v18, -0.5, v18
	v_mul_f32_e32 v18, 0x3fb8aa3b, v18
	v_add_f32_e32 v42, 1.0, v42
	v_cmp_gt_f32_e32 vcc, s30, v42
	v_exp_f32_e32 v18, v18
	v_mov_b32_e32 v73, v78
	v_cndmask_b32_e64 v44, 0, 32, vcc
	v_ldexp_f32 v42, v42, v44
	v_log_f32_e32 v44, v42
	v_mul_f32_e32 v18, 0xbfb8aa3b, v18
	v_exp_f32_e32 v18, v18
	v_add_u32_e32 v42, 0xc0, v61
	v_mul_f32_e32 v48, 0x3f317217, v44
	v_fma_f32 v48, v44, s0, -v48
	v_fmac_f32_e32 v48, 0x3377d1cf, v44
	v_fmac_f32_e32 v48, 0x3f317217, v44
	v_cmp_lt_f32_e64 s[66:67], |v44|, s1
	s_nop 1
	v_cndmask_b32_e64 v44, v44, v48, s[66:67]
	v_cndmask_b32_e32 v48, 0, v228, vcc
	v_sub_f32_e32 v44, v44, v48
	v_add_f32_e32 v39, v39, v44
	v_add_f32_e32 v44, v107, v120
	v_mul_f32_e64 v48, |v44|, s16
	v_exp_f32_e32 v48, v48
	v_max_f32_e64 v44, -v44, 0
	v_sub_f32_e32 v39, -0.5, v39
	v_mul_f32_e32 v39, 0x3fb8aa3b, v39
	v_add_f32_e32 v48, 1.0, v48
	v_exp_f32_e32 v39, v39
	s_nop 0
	v_log_f32_e32 v48, v48
	v_mul_f32_e32 v39, 0xbfb8aa3b, v39
	v_exp_f32_e32 v39, v39
	v_mul_f32_e32 v54, 0x3f317217, v48
	v_fma_f32 v54, v48, s0, -v54
	v_fmac_f32_e32 v54, 0x3377d1cf, v48
	v_fmac_f32_e32 v54, 0x3f317217, v48
	v_mul_f32_e32 v39, v18, v39
	s_nop 0
	v_mov_b32_e32 v48, v54
	v_add_f32_e32 v44, v44, v48
	v_add_f32_e32 v48, 1.0, v56
	v_sub_f32_e32 v44, -0.5, v44
	v_mul_f32_e32 v44, 0x3fb8aa3b, v44
	v_log_f32_e32 v48, v48
	v_max_f32_e64 v54, -v55, 0
	v_exp_f32_e32 v44, v44
	v_mul_f32_e32 v55, 0x3f317217, v48
	v_fma_f32 v55, v48, s0, -v55
	v_fmac_f32_e32 v55, 0x3377d1cf, v48
	v_fmac_f32_e32 v55, 0x3f317217, v48
	v_mul_f32_e32 v44, 0xbfb8aa3b, v44
	v_exp_f32_e32 v44, v44
	v_mov_b32_e32 v48, v55
	v_add_f32_e32 v48, v54, v48
	v_sub_f32_e32 v48, -0.5, v48
	v_mul_f32_e32 v48, 0x3fb8aa3b, v48
	v_exp_f32_e32 v48, v48
	v_mul_f32_e32 v44, v44, v39
	s_mov_b64 s[0:1], 0x2000
	v_lshl_add_u64 v[54:55], v[80:81], 0, s[0:1]
	v_mul_f32_e32 v48, 0xbfb8aa3b, v48
	v_exp_f32_e32 v48, v48
	s_mov_b64 s[0:1], 0x2800
	v_lshl_add_u64 v[56:57], v[80:81], 0, s[0:1]
	s_mov_b64 s[0:1], 0x1800
	v_mul_f32_e32 v48, v48, v44
	ds_bpermute_b32 v60, v34, v48
	ds_bpermute_b32 v62, v40, v48
	ds_bpermute_b32 v63, v42, v48
	ds_bpermute_b32 v66, v67, v48
	v_lshl_add_u64 v[58:59], v[80:81], 0, s[0:1]
	s_waitcnt lgkmcnt(3)
; __device__ __forceinline__ unsigned pk2(float lo, float hi) { const bf16x2_t r = __builtin_convertvector((f32x2){lo, hi}, bf16x2_t); return __builtin_bit_cast(unsigned, r); }
; __device__ __forceinline__ float softplusf_(float x) { return fmaxf(x, 0.f) + __logf(1.f + __expf(-fabsf(x))); }
; __device__ __forceinline__ bf16 bf1(float x) { return (bf16)(pk2(x, x) & 0xffffu); }
; __device__ __forceinline__ void rwkv_prep_item(KArgs a, int l, int item, LAS unsigned char* lds, int tid, int lane, int wave) {
;     ...
;             Wd[0][i][nt] = __expf(-__expf(-softplusf_(-(w0f[nt] + acc[0][nt][i])) - 0.5f)); Wd[1][i][nt] = __expf(-__expf(-softplusf_(-(w0b[nt] + acc[1][nt][i])) - 0.5f));
;     ...
;             float tot = G * __int_as_float(__builtin_amdgcn_ds_bpermute((lane ^ 16) << 2, __float_as_int(G)));
;             tot = tot * __int_as_float(__builtin_amdgcn_ds_bpermute((lane ^ 32) << 2, __float_as_int(tot)));
;             float ap[4], kp[4];
; #pragma unroll
;             for (int i = 0; i < 4; ++i) { const int td = d ? 15 - (4 * fq + i) : 4 * fq + i; const float ig = __builtin_amdgcn_rcpf(gam[i]);
;                 const float at_ = Ka[i][nt] * ig, kt_ = Km[i][nt] * ig; ap[i] = at_ * tot; kp[i] = kt_ * tot;
;                 NTl[td * 68 + 16 * nt + fr] = bf1(gpv[i] * Nn[i][nt]); RTl[td * 68 + 16 * nt + fr] = bf1(gam[i] * Rr[i][nt]);
;                 ATl[td * 68 + 16 * nt + fr] = bf1(at_); KTl[td * 68 + 16 * nt + fr] = bf1(kt_); }
;             v2u pa, pk, pv;
;             if (d == 0) { pa = (v2u){pk2(ap[0], ap[1]), pk2(ap[2], ap[3])}; pk = (v2u){pk2(kp[0], kp[1]), pk2(kp[2], kp[3])}; pv = (v2u){pk2(Vv[0][nt], Vv[1][nt]), pk2(Vv[2][nt], Vv[3][nt])}; }
;             else { pa = (v2u){pk2(ap[3], ap[2]), pk2(ap[1], ap[0])}; pk = (v2u){pk2(kp[3], kp[2]), pk2(kp[1], kp[0])}; pv = (v2u){pk2(Vv[3][nt], Vv[2][nt]), pk2(Vv[1][nt], Vv[0][nt])}; }
;             *(v2u*)(img + RCH_APT + nt * 512 + laneD * 8) = pa; *(v2u*)(img + RCH_KPT + nt * 512 + laneD * 8) = pk; *(v2u*)(img + RCH_VM + nt * 512 + laneD * 8) = pv;
;             if (fq == 0) *(float*)(img + RCH_GC + (16 * nt + fr) * 4) = tot;
	v_cndmask_b32_e64 v60, 1.0, v60, s[40:41]
	s_waitcnt lgkmcnt(2)
	v_cndmask_b32_e64 v62, 1.0, v62, s[62:63]
	v_mul_f32_e32 v60, v60, v62
	s_waitcnt lgkmcnt(1)
	v_cndmask_b32_e64 v62, 1.0, v63, s[64:65]
	v_mul_f32_e32 v60, v60, v62
	s_waitcnt lgkmcnt(0)
	v_mul_f32_e32 v62, v48, v66
	ds_bpermute_b32 v63, v7, v62
	v_mul_f32_e32 v44, v44, v60
	v_mul_f32_e32 v66, v39, v60
	v_mul_f32_e32 v39, v48, v60
	v_mul_f32_e32 v77, v18, v60
	s_waitcnt lgkmcnt(0)
	v_mul_f32_e32 v18, v62, v63
	v_rcp_f32_e32 v63, v39
	v_rcp_f32_e32 v62, v44
	v_mul_f32_e32 v39, v85, v39
	v_cvt_pk_bf16_f32 v39, v39, s0
	ds_write_b16 v86, v39 offset:2208
	v_pk_mul_f32 v[72:73], v[72:73], v[62:63]
	v_mul_f32_e64 v48, v44, -v127
	v_cvt_pk_bf16_f32 v39, v73, s0
	ds_write_b16 v86, v39 offset:4384
	v_mov_b32_e32 v39, v33
	v_pk_mul_f32 v[38:39], v[38:39], v[62:63]
	v_cvt_pk_bf16_f32 v48, v48, s0
	v_cvt_pk_bf16_f32 v33, v39, s0
	ds_write_b16 v86, v33 offset:6560
	v_mul_f32_e64 v33, v66, -v126
	v_cvt_pk_bf16_f32 v33, v33, s0
	ds_write_b16 v86, v48 offset:32
	ds_write_b16 v76, v33 offset:32
	v_mul_f32_e32 v33, v37, v44
	v_cvt_pk_bf16_f32 v33, v33, s0
	ds_write_b16 v76, v33 offset:2208
	v_cvt_pk_bf16_f32 v33, v72, s0
	v_pk_mul_f32 v[62:63], v[18:19], v[38:39] op_sel_hi:[0,1]
	ds_write_b16 v76, v33 offset:4384
	v_cvt_pk_bf16_f32 v33, v38, s0
	v_rcp_f32_e32 v39, v66
	v_rcp_f32_e32 v38, v77
	ds_write_b16 v76, v33 offset:6560
	v_mul_f32_e64 v33, v77, -v125
	v_cvt_pk_bf16_f32 v33, v33, s0
	v_pk_mul_f32 v[78:79], v[18:19], v[72:73] op_sel_hi:[0,1]
	ds_write_b16 v36, v33 offset:32
	v_mul_f32_e32 v33, v43, v66
	v_mov_b32_e32 v72, v75
	v_mov_b32_e32 v73, v74
	v_cvt_pk_bf16_f32 v33, v33, s0
	v_pk_mul_f32 v[72:73], v[72:73], v[38:39]
	v_mov_b32_e32 v80, v17
	v_mov_b32_e32 v81, v16
	ds_write_b16 v36, v33 offset:2208
	v_cvt_pk_bf16_f32 v33, v73, s0
	v_pk_mul_f32 v[16:17], v[80:81], v[38:39]
	ds_write_b16 v36, v33 offset:4384
	v_cvt_pk_bf16_f32 v33, v17, s0
	v_pk_mul_f32 v[38:39], v[18:19], v[16:17] op_sel_hi:[0,1]
	v_mul_f32_e64 v17, v60, -v122
	ds_write_b16 v36, v33 offset:6560
	v_cvt_pk_bf16_f32 v33, v17, s0
	v_add_u32_e32 v17, v31, v0
	v_mul_f32_e32 v31, v45, v77
	v_pk_mul_f32 v[74:75], v[18:19], v[72:73] op_sel_hi:[0,1]
	v_lshl_add_u32 v17, v17, 1, s25
	v_cvt_pk_bf16_f32 v31, v31, s0
	ds_write_b16 v17, v31 offset:2208
	v_cvt_pk_bf16_f32 v31, v72, s0
	v_cvt_pk_bf16_f32 v16, v16, s0
	v_cvt_pk_bf16_f32 v44, v49, v41
	v_cvt_pk_bf16_f32 v48, v74, v75
	v_cvt_pk_bf16_f32 v49, v78, v79
	ds_write_b16 v17, v33 offset:32
	ds_write_b16 v17, v31 offset:4384
	ds_write_b16 v17, v16 offset:6560
	v_cvt_pk_bf16_f32 v45, v35, v83
	v_cvt_pk_bf16_f32 v38, v38, v39
	v_cvt_pk_bf16_f32 v39, v62, v63
	global_store_dwordx2 v[54:55], v[48:49], off offset:512
	global_store_dwordx2 v[56:57], v[38:39], off offset:512
	global_store_dwordx2 v[58:59], v[44:45], off offset:512
	s_and_saveexec_b64 s[0:1], s[44:45]
	s_cbranch_execz .LBB0_846
	global_store_dword v61, v18, s[70:71] offset:64
.LBB0_846:
	s_or_b64 exec, exec, s[0:1]
	v_add_f32_e32 v16, v105, v117
	v_max_f32_e64 v18, -v16, 0
	v_mul_f32_e64 v16, |v16|, s16
	v_exp_f32_e32 v16, v16
	s_mov_b32 s0, 0x3f317217
	s_mov_b32 s1, 0x7f800000
	v_mov_b32_e32 v44, v71
	v_add_f32_e32 v16, 1.0, v16
	v_mov_b32_e32 v45, v70
	s_nop 0
	v_log_f32_e32 v16, v16
	s_nop 0
	v_mul_f32_e32 v31, 0x3f317217, v16
	v_fma_f32 v31, v16, s0, -v31
	v_fmac_f32_e32 v31, 0x3377d1cf, v16
	v_fmac_f32_e32 v31, 0x3f317217, v16
	s_nop 1
	v_mov_b32_e32 v16, v31
	v_add_f32_e32 v16, v18, v16
	v_add_f32_e32 v18, v104, v117
	v_max_f32_e64 v31, -v18, 0
	v_mul_f32_e64 v18, |v18|, s16
	v_exp_f32_e32 v18, v18
	v_sub_f32_e32 v16, -0.5, v16
	v_mul_f32_e32 v16, 0x3fb8aa3b, v16
	v_exp_f32_e32 v16, v16
	v_add_f32_e32 v18, 1.0, v18
	v_mul_f32_e32 v16, 0xbfb8aa3b, v16
	s_nop 0
	v_log_f32_e32 v18, v18
	v_exp_f32_e32 v16, v16
	v_mul_f32_e32 v33, 0x3f317217, v18
	v_fma_f32 v33, v18, s0, -v33
	v_fmac_f32_e32 v33, 0x3377d1cf, v18
	v_fmac_f32_e32 v33, 0x3f317217, v18
	s_nop 1
	v_mov_b32_e32 v18, v33
	v_add_f32_e32 v18, v31, v18
	v_add_f32_e32 v31, v103, v117
	v_max_f32_e64 v33, -v31, 0
	v_mul_f32_e64 v31, |v31|, s16
	v_exp_f32_e32 v31, v31
	v_sub_f32_e32 v18, -0.5, v18
	v_mul_f32_e32 v18, 0x3fb8aa3b, v18
	v_exp_f32_e32 v18, v18
	v_add_f32_e32 v31, 1.0, v31
	v_mul_f32_e32 v18, 0xbfb8aa3b, v18
	s_nop 0
	v_log_f32_e32 v31, v31
	v_exp_f32_e32 v18, v18
	v_mul_f32_e32 v35, 0x3f317217, v31
	v_fma_f32 v35, v31, s0, -v35
	v_fmac_f32_e32 v35, 0x3377d1cf, v31
	v_fmac_f32_e32 v35, 0x3f317217, v31
	v_mul_f32_e32 v18, v16, v18
	s_nop 0
	v_mov_b32_e32 v31, v35
	v_add_f32_e32 v31, v33, v31
	v_add_f32_e32 v33, v102, v117
	v_max_f32_e64 v35, -v33, 0
	v_mul_f32_e64 v33, |v33|, s16
	v_exp_f32_e32 v33, v33
	v_sub_f32_e32 v31, -0.5, v31
	v_mul_f32_e32 v31, 0x3fb8aa3b, v31
	v_exp_f32_e32 v31, v31
	v_add_f32_e32 v33, 1.0, v33
	v_mul_f32_e32 v31, 0xbfb8aa3b, v31
	s_nop 0
	v_log_f32_e32 v33, v33
	v_exp_f32_e32 v31, v31
	v_mul_f32_e32 v37, 0x3f317217, v33
	v_fma_f32 v37, v33, s0, -v37
	v_fmac_f32_e32 v37, 0x3377d1cf, v33
	v_fmac_f32_e32 v37, 0x3f317217, v33
	v_mul_f32_e32 v31, v31, v18
	s_nop 0
	v_mov_b32_e32 v33, v37
	v_add_f32_e32 v33, v35, v33
	v_sub_f32_e32 v33, -0.5, v33
	v_mul_f32_e32 v33, 0x3fb8aa3b, v33
	v_exp_f32_e32 v33, v33
	s_nop 0
	v_mul_f32_e32 v33, 0xbfb8aa3b, v33
	v_exp_f32_e32 v33, v33
	s_nop 0
	v_mul_f32_e32 v33, v33, v31
	ds_bpermute_b32 v35, v34, v33
	ds_bpermute_b32 v37, v40, v33
	ds_bpermute_b32 v38, v42, v33
	s_waitcnt lgkmcnt(2)
	v_cndmask_b32_e64 v35, 1.0, v35, s[40:41]
	s_waitcnt lgkmcnt(1)
	v_cndmask_b32_e64 v37, 1.0, v37, s[62:63]
	v_mul_f32_e32 v35, v35, v37
	s_waitcnt lgkmcnt(0)
; __device__ __forceinline__ unsigned pk2(float lo, float hi) { const bf16x2_t r = __builtin_convertvector((f32x2){lo, hi}, bf16x2_t); return __builtin_bit_cast(unsigned, r); }
; __device__ __forceinline__ bf16 bf1(float x) { return (bf16)(pk2(x, x) & 0xffffu); }
; __device__ __forceinline__ void rwkv_prep_item(KArgs a, int l, int item, LAS unsigned char* lds, int tid, int lane, int wave) {
;     ...
;             float tot = G * __int_as_float(__builtin_amdgcn_ds_bpermute((lane ^ 16) << 2, __float_as_int(G)));
;             tot = tot * __int_as_float(__builtin_amdgcn_ds_bpermute((lane ^ 32) << 2, __float_as_int(tot)));
;             float ap[4], kp[4];
; #pragma unroll
;             for (int i = 0; i < 4; ++i) { const int td = d ? 15 - (4 * fq + i) : 4 * fq + i; const float ig = __builtin_amdgcn_rcpf(gam[i]);
;                 const float at_ = Ka[i][nt] * ig, kt_ = Km[i][nt] * ig; ap[i] = at_ * tot; kp[i] = kt_ * tot;
;                 NTl[td * 68 + 16 * nt + fr] = bf1(gpv[i] * Nn[i][nt]); RTl[td * 68 + 16 * nt + fr] = bf1(gam[i] * Rr[i][nt]);
;                 ATl[td * 68 + 16 * nt + fr] = bf1(at_); KTl[td * 68 + 16 * nt + fr] = bf1(kt_); }
;             v2u pa, pk, pv;
;             if (d == 0) { pa = (v2u){pk2(ap[0], ap[1]), pk2(ap[2], ap[3])}; pk = (v2u){pk2(kp[0], kp[1]), pk2(kp[2], kp[3])}; pv = (v2u){pk2(Vv[0][nt], Vv[1][nt]), pk2(Vv[2][nt], Vv[3][nt])}; }
;             else { pa = (v2u){pk2(ap[3], ap[2]), pk2(ap[1], ap[0])}; pk = (v2u){pk2(kp[3], kp[2]), pk2(kp[1], kp[0])}; pv = (v2u){pk2(Vv[3][nt], Vv[2][nt]), pk2(Vv[1][nt], Vv[0][nt])}; }
;             *(v2u*)(img + RCH_APT + nt * 512 + laneD * 8) = pa; *(v2u*)(img + RCH_KPT + nt * 512 + laneD * 8) = pk; *(v2u*)(img + RCH_VM + nt * 512 + laneD * 8) = pv;
;             if (fq == 0) *(float*)(img + RCH_GC + (16 * nt + fr) * 4) = tot;
	v_cndmask_b32_e64 v37, 1.0, v38, s[64:65]
	v_mul_f32_e32 v35, v35, v37
	v_mul_f32_e32 v41, v16, v35
	ds_bpermute_b32 v16, v67, v33
	v_mul_f32_e32 v37, v31, v35
	v_mul_f32_e32 v31, v33, v35
	v_rcp_f32_e32 v39, v31
	v_rcp_f32_e32 v38, v37
	s_waitcnt lgkmcnt(0)
	v_mul_f32_e32 v16, v33, v16
	ds_bpermute_b32 v33, v7, v16
	v_mul_f32_e32 v31, v50, v31
	v_cvt_pk_bf16_f32 v31, v31, s0
	v_pk_mul_f32 v[44:45], v[44:45], v[38:39]
	ds_write_b16 v86, v31 offset:2240
	v_cvt_pk_bf16_f32 v31, v45, s0
	ds_write_b16 v86, v31 offset:4416
	v_mov_b32_e32 v31, v29
	s_waitcnt lgkmcnt(2)
	v_mul_f32_e32 v16, v16, v33
	v_mul_f32_e64 v33, v37, -v119
	v_pk_mul_f32 v[30:31], v[30:31], v[38:39]
	v_mul_f32_e32 v20, v20, v37
	v_cvt_pk_bf16_f32 v33, v33, s0
	v_cvt_pk_bf16_f32 v29, v31, s0
	v_cvt_pk_bf16_f32 v20, v20, s0
	v_mul_f32_e32 v18, v18, v35
	ds_write_b16 v86, v33 offset:64
	ds_write_b16 v86, v29 offset:6592
	ds_write_b16 v76, v20 offset:2240
	v_cvt_pk_bf16_f32 v20, v44, s0
	v_pk_mul_f32 v[38:39], v[16:17], v[30:31] op_sel_hi:[0,1]
	ds_write_b16 v76, v20 offset:4416
	v_cvt_pk_bf16_f32 v20, v30, s0
	v_rcp_f32_e32 v31, v18
	v_rcp_f32_e32 v30, v41
	v_pk_mul_f32 v[48:49], v[16:17], v[44:45] op_sel_hi:[0,1]
	v_mul_f32_e64 v29, v18, -v118
	v_mul_f32_e32 v10, v10, v18
	v_mov_b32_e32 v44, v69
	v_mov_b32_e32 v45, v68
	v_cvt_pk_bf16_f32 v29, v29, s0
	v_cvt_pk_bf16_f32 v10, v10, s0
	v_pk_mul_f32 v[44:45], v[44:45], v[30:31]
	v_mov_b32_e32 v68, v13
	v_mov_b32_e32 v69, v12
	ds_write_b16 v76, v29 offset:64
	ds_write_b16 v76, v20 offset:6592
	ds_write_b16 v36, v10 offset:2240
	v_cvt_pk_bf16_f32 v10, v45, s0
	v_pk_mul_f32 v[12:13], v[68:69], v[30:31]
	ds_write_b16 v36, v10 offset:4416
	v_cvt_pk_bf16_f32 v10, v13, s0
	v_mul_f32_e64 v20, v41, -v115
	ds_write_b16 v36, v10 offset:6592
	v_mul_f32_e64 v10, v35, -v114
	v_cvt_pk_bf16_f32 v20, v20, s0
	v_cvt_pk_bf16_f32 v10, v10, s0
	ds_write_b16 v36, v20 offset:64
	ds_write_b16 v17, v10 offset:64
	v_mul_f32_e32 v10, v24, v41
	v_cvt_pk_bf16_f32 v10, v10, s0
	v_pk_mul_f32 v[62:63], v[16:17], v[44:45] op_sel_hi:[0,1]
	v_pk_mul_f32 v[30:31], v[16:17], v[12:13] op_sel_hi:[0,1]
	ds_write_b16 v17, v10 offset:2240
	v_cvt_pk_bf16_f32 v10, v44, s0
	ds_write_b16 v17, v10 offset:4416
	v_cvt_pk_bf16_f32 v10, v12, s0
	v_cvt_pk_bf16_f32 v30, v30, v31
	v_cvt_pk_bf16_f32 v31, v38, v39
	v_cvt_pk_bf16_f32 v38, v62, v63
	v_cvt_pk_bf16_f32 v39, v48, v49
	ds_write_b16 v17, v10 offset:6592
	v_cvt_pk_bf16_f32 v12, v26, v14
	v_cvt_pk_bf16_f32 v13, v22, v46
	global_store_dwordx2 v[54:55], v[38:39], off offset:1024
	global_store_dwordx2 v[56:57], v[30:31], off offset:1024
	global_store_dwordx2 v[58:59], v[12:13], off offset:1024
	s_and_saveexec_b64 s[0:1], s[44:45]
	s_cbranch_execz .LBB0_848
	global_store_dword v61, v16, s[70:71] offset:128
; __device__ __forceinline__ unsigned pk2(float lo, float hi) { const bf16x2_t r = __builtin_convertvector((f32x2){lo, hi}, bf16x2_t); return __builtin_bit_cast(unsigned, r); }
; __device__ __forceinline__ float softplusf_(float x) { return fmaxf(x, 0.f) + __logf(1.f + __expf(-fabsf(x))); }
; __device__ __forceinline__ bf16 bf1(float x) { return (bf16)(pk2(x, x) & 0xffffu); }
; __device__ __forceinline__ void rwkv_prep_item(KArgs a, int l, int item, LAS unsigned char* lds, int tid, int lane, int wave) {
;     ...
;             Wd[0][i][nt] = __expf(-__expf(-softplusf_(-(w0f[nt] + acc[0][nt][i])) - 0.5f)); Wd[1][i][nt] = __expf(-__expf(-softplusf_(-(w0b[nt] + acc[1][nt][i])) - 0.5f));
;     ...
;             float tot = G * __int_as_float(__builtin_amdgcn_ds_bpermute((lane ^ 16) << 2, __float_as_int(G)));
;             tot = tot * __int_as_float(__builtin_amdgcn_ds_bpermute((lane ^ 32) << 2, __float_as_int(tot)));
;             float ap[4], kp[4];
; #pragma unroll
;             for (int i = 0; i < 4; ++i) { const int td = d ? 15 - (4 * fq + i) : 4 * fq + i; const float ig = __builtin_amdgcn_rcpf(gam[i]);
;                 const float at_ = Ka[i][nt] * ig, kt_ = Km[i][nt] * ig; ap[i] = at_ * tot; kp[i] = kt_ * tot;
;                 NTl[td * 68 + 16 * nt + fr] = bf1(gpv[i] * Nn[i][nt]); RTl[td * 68 + 16 * nt + fr] = bf1(gam[i] * Rr[i][nt]);
;                 ATl[td * 68 + 16 * nt + fr] = bf1(at_); KTl[td * 68 + 16 * nt + fr] = bf1(kt_); }
;             v2u pa, pk, pv;
;             if (d == 0) { pa = (v2u){pk2(ap[0], ap[1]), pk2(ap[2], ap[3])}; pk = (v2u){pk2(kp[0], kp[1]), pk2(kp[2], kp[3])}; pv = (v2u){pk2(Vv[0][nt], Vv[1][nt]), pk2(Vv[2][nt], Vv[3][nt])}; }
;             else { pa = (v2u){pk2(ap[3], ap[2]), pk2(ap[1], ap[0])}; pk = (v2u){pk2(kp[3], kp[2]), pk2(kp[1], kp[0])}; pv = (v2u){pk2(Vv[3][nt], Vv[2][nt]), pk2(Vv[1][nt], Vv[0][nt])}; }
;             *(v2u*)(img + RCH_APT + nt * 512 + laneD * 8) = pa; *(v2u*)(img + RCH_KPT + nt * 512 + laneD * 8) = pk; *(v2u*)(img + RCH_VM + nt * 512 + laneD * 8) = pv;
;             if (fq == 0) *(float*)(img + RCH_GC + (16 * nt + fr) * 4) = tot;
.LBB0_848:
	s_or_b64 exec, exec, s[0:1]
	v_add_f32_e32 v10, v101, v116
	v_max_f32_e64 v12, -v10, 0
	v_mul_f32_e64 v10, |v10|, s16
	v_exp_f32_e32 v10, v10
	s_mov_b32 s0, 0x3f317217
	s_mov_b32 s1, 0x7f800000
	v_add_f32_e32 v10, 1.0, v10
	s_nop 1
	v_log_f32_e32 v10, v10
	s_nop 0
	v_mul_f32_e32 v13, 0x3f317217, v10
	v_fma_f32 v13, v10, s0, -v13
	v_fmac_f32_e32 v13, 0x3377d1cf, v10
	v_fmac_f32_e32 v13, 0x3f317217, v10
	s_nop 1
	v_mov_b32_e32 v10, v13
	v_add_f32_e32 v10, v12, v10
	v_add_f32_e32 v12, v100, v116
	v_max_f32_e64 v13, -v12, 0
	v_mul_f32_e64 v12, |v12|, s16
	v_exp_f32_e32 v12, v12
	v_sub_f32_e32 v10, -0.5, v10
	v_mul_f32_e32 v10, 0x3fb8aa3b, v10
	v_exp_f32_e32 v10, v10
	v_add_f32_e32 v12, 1.0, v12
	v_mul_f32_e32 v10, 0xbfb8aa3b, v10
	s_nop 0
	v_log_f32_e32 v12, v12
	v_exp_f32_e32 v10, v10
	v_mul_f32_e32 v14, 0x3f317217, v12
	v_fma_f32 v14, v12, s0, -v14
	v_fmac_f32_e32 v14, 0x3377d1cf, v12
	v_fmac_f32_e32 v14, 0x3f317217, v12
	s_nop 1
	v_mov_b32_e32 v12, v14
	v_add_f32_e32 v12, v13, v12
	v_add_f32_e32 v13, v99, v116
	v_max_f32_e64 v14, -v13, 0
	v_mul_f32_e64 v13, |v13|, s16
	v_exp_f32_e32 v13, v13
	v_sub_f32_e32 v12, -0.5, v12
	v_mul_f32_e32 v12, 0x3fb8aa3b, v12
	v_exp_f32_e32 v12, v12
	v_add_f32_e32 v13, 1.0, v13
	v_mul_f32_e32 v12, 0xbfb8aa3b, v12
	s_nop 0
	v_log_f32_e32 v13, v13
	v_exp_f32_e32 v12, v12
	v_mul_f32_e32 v16, 0x3f317217, v13
	v_fma_f32 v16, v13, s0, -v16
	v_fmac_f32_e32 v16, 0x3377d1cf, v13
	v_fmac_f32_e32 v16, 0x3f317217, v13
	v_mul_f32_e32 v12, v10, v12
	s_nop 0
	v_mov_b32_e32 v13, v16
	v_add_f32_e32 v13, v14, v13
	v_add_f32_e32 v14, v98, v116
	v_max_f32_e64 v16, -v14, 0
	v_mul_f32_e64 v14, |v14|, s16
	v_exp_f32_e32 v14, v14
	v_sub_f32_e32 v13, -0.5, v13
	v_mul_f32_e32 v13, 0x3fb8aa3b, v13
	v_exp_f32_e32 v13, v13
	v_add_f32_e32 v14, 1.0, v14
	v_mul_f32_e32 v13, 0xbfb8aa3b, v13
	s_nop 0
	v_log_f32_e32 v14, v14
	v_exp_f32_e32 v13, v13
	v_mul_f32_e32 v18, 0x3f317217, v14
	v_fma_f32 v18, v14, s0, -v18
	v_fmac_f32_e32 v18, 0x3377d1cf, v14
	v_fmac_f32_e32 v18, 0x3f317217, v14
	v_mul_f32_e32 v13, v13, v12
	s_nop 0
	v_mov_b32_e32 v14, v18
	v_add_f32_e32 v14, v16, v14
	v_sub_f32_e32 v14, -0.5, v14
	v_mul_f32_e32 v14, 0x3fb8aa3b, v14
	v_exp_f32_e32 v14, v14
	s_nop 0
	v_mul_f32_e32 v14, 0xbfb8aa3b, v14
	v_exp_f32_e32 v14, v14
	s_nop 0
	v_mul_f32_e32 v14, v14, v13
	ds_bpermute_b32 v16, v34, v14
	ds_bpermute_b32 v18, v40, v14
	ds_bpermute_b32 v20, v42, v14
	s_waitcnt lgkmcnt(2)
	v_cndmask_b32_e64 v16, 1.0, v16, s[40:41]
	s_waitcnt lgkmcnt(1)
	v_cndmask_b32_e64 v18, 1.0, v18, s[62:63]
	v_mul_f32_e32 v16, v16, v18
	s_waitcnt lgkmcnt(0)
	v_cndmask_b32_e64 v18, 1.0, v20, s[64:65]
	v_mul_f32_e32 v16, v16, v18
	v_mul_f32_e32 v22, v10, v16
	ds_bpermute_b32 v10, v67, v14
	v_mul_f32_e32 v18, v13, v16
	v_mul_f32_e32 v20, v12, v16
	v_mul_f32_e32 v12, v14, v16
	v_rcp_f32_e32 v13, v12
	s_waitcnt lgkmcnt(0)
	v_mul_f32_e32 v10, v14, v10
	ds_bpermute_b32 v7, v7, v10
	v_cvt_pk_bf16_f32 v14, v27, v15
	v_cvt_pk_bf16_f32 v15, v23, v47
	v_mov_b32_e32 v23, v8
	s_waitcnt lgkmcnt(0)
	v_mul_f32_e32 v10, v10, v7
	v_mul_f32_e64 v7, v18, -v91
	v_cvt_pk_bf16_f32 v7, v7, s0
	ds_write_b16 v86, v7 offset:96
	v_mul_f32_e32 v7, v51, v12
	v_cvt_pk_bf16_f32 v7, v7, s0
	ds_write_b16 v86, v7 offset:2272
	v_mul_f32_e64 v7, v20, -v90
	v_cvt_pk_bf16_f32 v24, v7, s0
	v_mul_f32_e32 v7, v21, v18
	v_cvt_pk_bf16_f32 v26, v7, s0
	v_mul_f32_e64 v7, v22, -v87
	v_rcp_f32_e32 v12, v18
	v_cvt_pk_bf16_f32 v29, v7, s0
	v_mul_f32_e32 v7, v11, v20
	v_rcp_f32_e32 v21, v20
	v_cvt_pk_bf16_f32 v11, v7, s0
	v_rcp_f32_e32 v20, v22
	v_mul_f32_e64 v7, v16, -v32
	v_cvt_pk_bf16_f32 v16, v7, s0
	v_mul_f32_e32 v7, v25, v22
	v_cvt_pk_bf16_f32 v25, v7, s0
	v_mov_b32_e32 v7, v19
	v_mov_b32_e32 v22, v9
	v_pk_mul_f32 v[6:7], v[6:7], v[12:13]
	v_pk_mul_f32 v[8:9], v[22:23], v[20:21]
	v_cvt_pk_bf16_f32 v18, v7, s0
	v_cvt_pk_bf16_f32 v22, v9, s0
	v_cvt_pk_bf16_f32 v23, v8, s0
	v_pk_mul_f32 v[8:9], v[10:11], v[8:9] op_sel_hi:[0,1]
	ds_write_b16 v86, v18 offset:6624
	v_cvt_pk_bf16_f32 v27, v6, s0
	v_pk_mul_f32 v[6:7], v[10:11], v[6:7] op_sel_hi:[0,1]
	v_mov_b32_e32 v18, v65
	v_mov_b32_e32 v19, v64
	v_cvt_pk_bf16_f32 v8, v8, v9
	v_cvt_pk_bf16_f32 v9, v6, v7
	v_mov_b32_e32 v6, v53
	v_mov_b32_e32 v7, v52
	v_pk_mul_f32 v[12:13], v[18:19], v[12:13]
	v_pk_mul_f32 v[6:7], v[6:7], v[20:21]
	v_cvt_pk_bf16_f32 v18, v13, s0
	v_cvt_pk_bf16_f32 v20, v7, s0
	v_cvt_pk_bf16_f32 v21, v6, s0
	v_pk_mul_f32 v[6:7], v[10:11], v[6:7] op_sel_hi:[0,1]
	ds_write_b16 v86, v18 offset:4448
	ds_write_b16 v76, v24 offset:96
	ds_write_b16 v76, v26 offset:2272
	v_cvt_pk_bf16_f32 v18, v12, s0
	v_pk_mul_f32 v[12:13], v[10:11], v[12:13] op_sel_hi:[0,1]
	v_cvt_pk_bf16_f32 v6, v6, v7
	v_cvt_pk_bf16_f32 v7, v12, v13
	ds_write_b16 v76, v18 offset:4448
	ds_write_b16 v76, v27 offset:6624
	ds_write_b16 v36, v29 offset:96
	ds_write_b16 v36, v11 offset:2272
	ds_write_b16 v36, v20 offset:4448
	ds_write_b16 v36, v22 offset:6624
	ds_write_b16 v17, v16 offset:96
	ds_write_b16 v17, v25 offset:2272
	ds_write_b16 v17, v21 offset:4448
	ds_write_b16 v17, v23 offset:6624
	global_store_dwordx2 v[54:55], v[6:7], off offset:1536
	global_store_dwordx2 v[56:57], v[8:9], off offset:1536
	global_store_dwordx2 v[58:59], v[14:15], off offset:1536
	s_and_saveexec_b64 s[0:1], s[44:45]
	s_cbranch_execz .LBB0_850
	global_store_dword v61, v10, s[70:71] offset:192
